# P7 EpiUp epilogue peepholes: dropped dead v_mov 0 old-value inits before full-row DPP movs and always-true row-validity cndmasks (197 VALU ops per tile)
# speedup vs baseline: 1.0101x; 1.0024x over previous
.LBB0_1414:
	s_or_b64 exec, exec, s[34:35]
	v_cmp_lt_i32_e64 s[28:29], 14, v220
	s_mov_b64 s[34:35], 0
	s_and_saveexec_b64 s[40:41], s[28:29]
	s_xor_b64 s[28:29], exec, s[40:41]
	s_mov_b64 s[34:35], exec
	s_or_saveexec_b64 s[28:29], s[28:29]
	s_lshl_b32 s8, s8, 13
	s_and_b32 s8, s8, 0x2000
	v_readlane_b32 s9, v253, 59
	s_waitcnt vmcnt(0)
	v_pk_fma_f32 v[138:139], v[138:139], v[146:147], v[98:99] op_sel_hi:[1,0,1]
	v_pk_fma_f32 v[136:137], v[136:137], v[146:147], v[96:97] op_sel_hi:[1,0,1]
	s_add_i32 s9, s9, s8
	v_cndmask_b32_e64 v163, 0, v139, s[20:21]
	v_cndmask_b32_e64 v162, 0, v138, s[20:21]
	v_cndmask_b32_e64 v161, 0, v137, s[20:21]
	v_cndmask_b32_e64 v160, 0, v136, s[20:21]
	v_pk_fma_f32 v[136:137], v[142:143], v[144:145], v[98:99] op_sel_hi:[1,0,1]
	v_pk_fma_f32 v[138:139], v[140:141], v[144:145], v[96:97] op_sel_hi:[1,0,1]
	s_add_i32 s8, s9, 0x400
	v_cndmask_b32_e32 v171, 0, v137, vcc
	v_cndmask_b32_e32 v170, 0, v136, vcc
	v_cndmask_b32_e32 v169, 0, v139, vcc
	v_cndmask_b32_e32 v168, 0, v138, vcc
	v_mov_b64_e32 v[136:137], v[160:161]
	v_mov_b32_e32 v140, s8
	v_mov_b64_e32 v[138:139], v[162:163]
	s_xor_b64 exec, exec, s[28:29]
	s_andn2_b64 s[34:35], s[34:35], exec
	s_and_b64 s[40:41], s[2:3], exec
	v_mov_b64_e32 v[136:137], v[168:169]
	v_mov_b32_e32 v140, s9
	s_or_b64 s[34:35], s[34:35], s[40:41]
	v_mov_b64_e32 v[138:139], v[170:171]
	s_or_b64 exec, exec, s[28:29]
	v_pk_fma_f32 v[90:91], v[90:91], v[150:151], v[98:99] op_sel_hi:[1,0,1]
	v_pk_fma_f32 v[88:89], v[88:89], v[150:151], v[96:97] op_sel_hi:[1,0,1]
	v_pk_fma_f32 v[18:19], v[18:19], v[150:151], v[26:27] op_sel_hi:[1,0,1]
	v_pk_fma_f32 v[16:17], v[16:17], v[150:151], v[24:25] op_sel_hi:[1,0,1]
	v_pk_fma_f32 v[94:95], v[94:95], v[150:151], v[102:103] op_sel_hi:[1,0,1]
	v_pk_fma_f32 v[92:93], v[92:93], v[150:151], v[100:101] op_sel_hi:[1,0,1]
	v_pk_fma_f32 v[22:23], v[22:23], v[150:151], v[30:31] op_sel_hi:[1,0,1]
	v_pk_fma_f32 v[20:21], v[20:21], v[150:151], v[28:29] op_sel_hi:[1,0,1]
	v_pk_fma_f32 v[126:127], v[126:127], v[148:149], v[98:99] op_sel_hi:[1,0,1]
	v_pk_fma_f32 v[124:125], v[124:125], v[148:149], v[96:97] op_sel_hi:[1,0,1]
	v_pk_fma_f32 v[54:55], v[54:55], v[148:149], v[26:27] op_sel_hi:[1,0,1]
	v_pk_fma_f32 v[52:53], v[52:53], v[148:149], v[24:25] op_sel_hi:[1,0,1]
	v_pk_fma_f32 v[122:123], v[122:123], v[148:149], v[102:103] op_sel_hi:[1,0,1]
	v_pk_fma_f32 v[120:121], v[120:121], v[148:149], v[100:101] op_sel_hi:[1,0,1]
	v_pk_fma_f32 v[50:51], v[50:51], v[148:149], v[30:31] op_sel_hi:[1,0,1]
	v_pk_fma_f32 v[48:49], v[48:49], v[148:149], v[28:29] op_sel_hi:[1,0,1]
	v_pk_fma_f32 v[58:59], v[58:59], v[146:147], v[26:27] op_sel_hi:[1,0,1]
	v_pk_fma_f32 v[56:57], v[56:57], v[146:147], v[24:25] op_sel_hi:[1,0,1]
	v_pk_fma_f32 v[134:135], v[134:135], v[146:147], v[102:103] op_sel_hi:[1,0,1]
	v_pk_fma_f32 v[132:133], v[132:133], v[146:147], v[100:101] op_sel_hi:[1,0,1]
	v_pk_fma_f32 v[62:63], v[62:63], v[146:147], v[30:31] op_sel_hi:[1,0,1]
	v_pk_fma_f32 v[60:61], v[60:61], v[146:147], v[28:29] op_sel_hi:[1,0,1]
	v_pk_fma_f32 v[86:87], v[86:87], v[144:145], v[26:27] op_sel_hi:[1,0,1]
	v_pk_fma_f32 v[84:85], v[84:85], v[144:145], v[24:25] op_sel_hi:[1,0,1]
	v_pk_fma_f32 v[130:131], v[130:131], v[144:145], v[102:103] op_sel_hi:[1,0,1]
	v_pk_fma_f32 v[128:129], v[128:129], v[144:145], v[100:101] op_sel_hi:[1,0,1]
	v_pk_fma_f32 v[82:83], v[82:83], v[144:145], v[30:31] op_sel_hi:[1,0,1]
	v_pk_fma_f32 v[80:81], v[80:81], v[144:145], v[28:29] op_sel_hi:[1,0,1]
	v_cndmask_b32_e64 v167, 0, v135, s[20:21]
	v_cndmask_b32_e64 v166, 0, v134, s[20:21]
	v_cndmask_b32_e64 v165, 0, v133, s[20:21]
	v_cndmask_b32_e64 v164, 0, v132, s[20:21]
	v_cndmask_b32_e32 v87, 0, v87, vcc
	v_cndmask_b32_e32 v86, 0, v86, vcc
	v_cndmask_b32_e32 v85, 0, v85, vcc
	v_cndmask_b32_e32 v84, 0, v84, vcc
	v_cndmask_b32_e32 v175, 0, v131, vcc
	v_cndmask_b32_e32 v174, 0, v130, vcc
	v_cndmask_b32_e32 v173, 0, v129, vcc
	v_cndmask_b32_e32 v172, 0, v128, vcc
	v_cndmask_b32_e32 v83, 0, v83, vcc
	v_cndmask_b32_e32 v82, 0, v82, vcc
	v_cndmask_b32_e32 v81, 0, v81, vcc
	v_cndmask_b32_e32 v80, 0, v80, vcc
	s_and_saveexec_b64 s[20:21], s[34:35]
	s_cbranch_execz .LBB0_1455
	v_lshl_add_u32 v128, v223, 2, v140
	ds_write_b128 v128, v[136:139]
	v_mov_b64_e32 v[130:131], v[58:59]
	v_cmp_gt_i32_e32 vcc, 15, v220
	s_mov_b64 s[24:25], -1
	v_mov_b32_e32 v132, s8
	v_mov_b64_e32 v[128:129], v[56:57]
	s_and_saveexec_b64 s[22:23], vcc
	s_cbranch_execz .LBB0_1423
	v_cmp_eq_u32_e32 vcc, 0, v220
	s_mov_b64 s[24:25], 0
	s_and_saveexec_b64 s[28:29], vcc
	s_mov_b64 s[24:25], exec
	s_or_b64 exec, exec, s[28:29]
	v_mov_b64_e32 v[130:131], v[86:87]
	v_mov_b32_e32 v132, s9
	s_orn2_b64 s[24:25], s[24:25], exec
	v_mov_b64_e32 v[128:129], v[84:85]

.LBB0_1457:
	v_pk_fma_f32 v[116:117], v[116:117], v[206:207], v[96:97] op_sel_hi:[1,0,1]
	v_pk_fma_f32 v[118:119], v[118:119], v[206:207], v[98:99] op_sel_hi:[1,0,1]
	v_cndmask_b32_e64 v218, 0, v116, s[18:19]
	v_cndmask_b32_e64 v219, 0, v117, s[18:19]
	v_cndmask_b32_e64 v117, v168, v218, s[2:3]
	v_cndmask_b32_e64 v216, 0, v118, s[18:19]
	v_cndmask_b32_e64 v118, v169, v219, s[2:3]
	v_mov_b32_dpp v116, v117 row_ror:15 row_mask:0xf bank_mask:0xf
	v_cndmask_b32_e64 v217, 0, v119, s[18:19]
	v_cndmask_b32_e64 v119, v170, v216, s[2:3]
	v_mov_b32_dpp v117, v118 row_ror:15 row_mask:0xf bank_mask:0xf
	v_mov_b32_e32 v205, 0
	v_mov_b32_dpp v118, v119 row_ror:15 row_mask:0xf bank_mask:0xf
	v_cndmask_b32_e64 v177, v171, v217, s[2:3]
	v_mov_b32_dpp v199, v168 row_ror:1 row_mask:0xf bank_mask:0xf
	v_mov_b32_dpp v201, v169 row_ror:1 row_mask:0xf bank_mask:0xf
	v_mov_b32_dpp v203, v170 row_ror:1 row_mask:0xf bank_mask:0xf
	v_mov_b32_dpp v205, v171 row_ror:1 row_mask:0xf bank_mask:0xf
	v_mov_b32_dpp v119, v177 row_ror:15 row_mask:0xf bank_mask:0xf
	s_and_b64 vcc, exec, s[20:21]
	v_mov_b32_e32 v177, 0
	v_mov_b32_e32 v178, 0
	v_mov_b32_e32 v179, 0
	s_mov_b64 s[62:63], s[24:25]
	s_mov_b64 s[66:67], s[28:29]
	s_cbranch_vccnz .LBB0_1459
	v_lshl_add_u32 v176, v225, 2, s8
	ds_read_b128 v[176:179], v176
.LBB0_1459:
	s_waitcnt lgkmcnt(0)
	v_cndmask_b32_e64 v180, v199, v180, s[2:3]
	v_cndmask_b32_e64 v181, v201, v181, s[2:3]
	v_cndmask_b32_e64 v182, v203, v182, s[2:3]
	v_cndmask_b32_e64 v183, v205, v183, s[2:3]
	s_waitcnt vmcnt(7)
	v_pk_mul_f32 v[180:181], v[156:157], v[180:181]
	v_mov_b32_e32 v207, v206
	v_pk_mul_f32 v[182:183], v[158:159], v[182:183]
	s_waitcnt vmcnt(6)
	v_pk_fma_f32 v[180:181], v[168:169], v[152:153], v[180:181]
	v_pk_fma_f32 v[182:183], v[170:171], v[154:155], v[182:183]
	s_waitcnt vmcnt(5)
	v_pk_fma_f32 v[116:117], v[148:149], v[116:117], v[180:181]
	v_mov_b32_e32 v180, v206
	v_mov_b32_e32 v181, v206
	v_pk_fma_f32 v[112:113], v[112:113], v[206:207], v[100:101]
	v_pk_fma_f32 v[118:119], v[150:151], v[118:119], v[182:183]
	v_pk_fma_f32 v[114:115], v[114:115], v[180:181], v[102:103]
	v_cndmask_b32_e64 v183, 0, v113, s[18:19]
	v_cndmask_b32_e64 v182, 0, v112, s[18:19]
	v_cndmask_b32_e64 v180, 0, v114, s[18:19]
	v_mov_b32_dpp v112, v172 row_ror:1 row_mask:0xf bank_mask:0xf
	v_mov_b32_dpp v113, v173 row_ror:1 row_mask:0xf bank_mask:0xf
	v_cndmask_b32_e64 v181, 0, v115, s[18:19]
	v_cndmask_b32_e64 v112, v112, v176, s[2:3]
	v_cndmask_b32_e64 v113, v113, v177, s[2:3]
	v_mov_b32_dpp v114, v174 row_ror:1 row_mask:0xf bank_mask:0xf
	v_cndmask_b32_e64 v177, v172, v182, s[2:3]
	v_cndmask_b32_e64 v114, v114, v178, s[2:3]
	v_mov_b32_dpp v115, v175 row_ror:1 row_mask:0xf bank_mask:0xf
	v_mov_b32_dpp v176, v177 row_ror:15 row_mask:0xf bank_mask:0xf
	v_cndmask_b32_e64 v178, v173, v183, s[2:3]
	v_cndmask_b32_e64 v115, v115, v179, s[2:3]
	v_cndmask_b32_e64 v179, v174, v180, s[2:3]
	v_mov_b32_dpp v177, v178 row_ror:15 row_mask:0xf bank_mask:0xf
	v_readlane_b32 s22, v253, 62
	v_cndmask_b32_e64 v199, v175, v181, s[2:3]
	v_mov_b32_dpp v178, v179 row_ror:15 row_mask:0xf bank_mask:0xf
	s_waitcnt vmcnt(3)
	v_pk_mul_f32 v[114:115], v[142:143], v[114:115]
	v_pk_mul_f32 v[112:113], v[140:141], v[112:113]
	v_readlane_b32 s23, v253, 63
	v_cmp_le_i32_e32 vcc, s42, v202
	v_mov_b32_dpp v179, v199 row_ror:15 row_mask:0xf bank_mask:0xf
	s_waitcnt vmcnt(2)
	v_pk_fma_f32 v[112:113], v[172:173], v[132:133], v[112:113]
	v_pk_fma_f32 v[114:115], v[174:175], v[134:135], v[114:115]
	s_and_b64 s[28:29], s[22:23], s[26:27]
	s_waitcnt vmcnt(1)
	v_pk_fma_f32 v[114:115], v[130:131], v[178:179], v[114:115]
	v_pk_fma_f32 v[112:113], v[128:129], v[176:177], v[112:113]
	s_or_b64 s[22:23], s[28:29], vcc
	v_pk_add_f32 v[118:119], v[146:147], v[118:119]
	v_pk_add_f32 v[116:117], v[144:145], v[116:117]
	s_waitcnt vmcnt(0)
	v_pk_add_f32 v[114:115], v[138:139], v[114:115]
	v_pk_add_f32 v[112:113], v[136:137], v[112:113]
	s_nor_b64 s[92:93], s[62:63], s[22:23]
	s_and_saveexec_b64 s[22:23], s[92:93]
	s_cbranch_execz .LBB0_1461
	v_mul_f32_e32 v176, 0xbfb8aa3b, v116
	v_mul_f32_e32 v177, 0xbfb8aa3b, v117
	v_mul_f32_e32 v178, 0xbfb8aa3b, v118
	v_mul_f32_e32 v179, 0xbfb8aa3b, v119
	v_exp_f32_e32 v176, v176
	v_exp_f32_e32 v177, v177
	v_exp_f32_e32 v178, v178
	v_exp_f32_e32 v179, v179
	v_add_f32_e32 v176, 1.0, v176
	v_add_f32_e32 v177, 1.0, v177
	v_add_f32_e32 v178, 1.0, v178
	v_add_f32_e32 v179, 1.0, v179
	v_rcp_f32_e32 v176, v176
	v_rcp_f32_e32 v177, v177
	v_rcp_f32_e32 v178, v178
	v_rcp_f32_e32 v179, v179
	v_pk_mul_f32 v[176:177], v[116:117], v[176:177]
	s_nop 0
	v_pk_mul_f32 v[176:177], v[176:177], v[112:113]
	v_pk_mul_f32 v[178:179], v[118:119], v[178:179]
	v_cvt_pk_bf16_f32 v176, v176, v177
	v_pk_mul_f32 v[178:179], v[178:179], v[114:115]
	s_nop 0
	v_cvt_pk_bf16_f32 v177, v178, v179
	v_mov_b64_e32 v[178:179], s[52:53]
	v_mad_i64_i32 v[178:179], s[24:25], v202, s39, v[178:179]
	v_lshl_add_u64 v[178:179], v[196:197], 1, v[178:179]
	global_store_dwordx2 v[178:179], v[176:177], off

.LBB0_1463:
	s_or_b64 exec, exec, s[22:23]
	v_pk_fma_f32 v[112:113], v[108:109], v[204:205], v[96:97] op_sel_hi:[1,0,1]
	v_pk_fma_f32 v[104:105], v[104:105], v[204:205], v[100:101] op_sel_hi:[1,0,1]
	v_cndmask_b32_e64 v114, 0, v112, s[16:17]
	v_cndmask_b32_e64 v112, 0, v104, s[16:17]
	v_cndmask_b32_e64 v104, v218, v168, s[0:1]
	v_mov_b32_e32 v117, 0
	v_mov_b32_e32 v178, 0
	v_mov_b32_dpp v116, v104 row_ror:1 row_mask:0xf bank_mask:0xf
	v_cndmask_b32_e64 v104, v219, v169, s[0:1]
	v_pk_fma_f32 v[110:111], v[110:111], v[204:205], v[98:99] op_sel_hi:[1,0,1]
	v_pk_fma_f32 v[106:107], v[106:107], v[204:205], v[102:103] op_sel_hi:[1,0,1]
	v_mov_b32_dpp v117, v104 row_ror:1 row_mask:0xf bank_mask:0xf
	v_cndmask_b32_e64 v104, v216, v170, s[0:1]
	v_mov_b32_e32 v179, 0
	v_cndmask_b32_e64 v108, 0, v110, s[16:17]
	v_mov_b32_dpp v178, v104 row_ror:1 row_mask:0xf bank_mask:0xf
	v_cndmask_b32_e64 v104, v217, v171, s[0:1]
	v_cndmask_b32_e64 v115, 0, v113, s[16:17]
	v_cndmask_b32_e64 v110, 0, v106, s[16:17]
	v_mov_b32_dpp v179, v104 row_ror:1 row_mask:0xf bank_mask:0xf
	v_cndmask_b32_e64 v104, v218, v114, s[2:3]
	v_cndmask_b32_e64 v109, 0, v111, s[16:17]
	v_cndmask_b32_e64 v111, 0, v107, s[16:17]
	v_mov_b32_dpp v106, v104 row_ror:15 row_mask:0xf bank_mask:0xf
	v_cndmask_b32_e64 v104, v219, v115, s[2:3]
	v_mov_b32_e32 v176, 0
	v_mov_b32_e32 v177, 0
	v_mov_b32_dpp v107, v104 row_ror:15 row_mask:0xf bank_mask:0xf
	v_cndmask_b32_e64 v104, v216, v108, s[2:3]
	v_cndmask_b32_e64 v113, 0, v105, s[16:17]
	v_cndmask_b32_e64 v105, v182, v172, s[0:1]
	v_mov_b32_dpp v176, v104 row_ror:15 row_mask:0xf bank_mask:0xf
	v_cndmask_b32_e64 v104, v217, v109, s[2:3]
	v_cndmask_b32_e64 v118, v183, v173, s[0:1]
	v_mov_b32_e32 v170, 0
	v_mov_b32_dpp v177, v104 row_ror:15 row_mask:0xf bank_mask:0xf
	v_cndmask_b32_e64 v119, v182, v112, s[2:3]
	v_mov_b32_dpp v104, v105 row_ror:1 row_mask:0xf bank_mask:0xf
	v_cndmask_b32_e64 v168, v183, v113, s[2:3]
	v_add_u32_e32 v199, s43, v227
	v_mov_b32_dpp v105, v118 row_ror:1 row_mask:0xf bank_mask:0xf
	v_cndmask_b32_e64 v118, v180, v174, s[0:1]
	v_cndmask_b32_e64 v169, v180, v110, s[2:3]
	v_cmp_gt_i32_e32 vcc, s42, v199
	v_mov_b32_dpp v170, v118 row_ror:1 row_mask:0xf bank_mask:0xf
	v_cndmask_b32_e64 v118, v181, v175, s[0:1]
	v_cndmask_b32_e64 v172, v181, v111, s[2:3]
	s_and_b64 s[94:95], s[66:67], vcc
	v_mov_b32_dpp v171, v118 row_ror:1 row_mask:0xf bank_mask:0xf
	s_nop 1
	v_mov_b32_dpp v118, v119 row_ror:15 row_mask:0xf bank_mask:0xf
	s_nop 1
	v_mov_b32_dpp v119, v168 row_ror:15 row_mask:0xf bank_mask:0xf
	s_nop 1
	v_mov_b32_dpp v168, v169 row_ror:15 row_mask:0xf bank_mask:0xf
	s_nop 1
	v_mov_b32_dpp v169, v172 row_ror:15 row_mask:0xf bank_mask:0xf
	s_and_saveexec_b64 s[22:23], s[94:95]
	s_cbranch_execz .LBB0_1465
	v_pk_mul_f32 v[116:117], v[156:157], v[116:117]
	v_pk_mul_f32 v[172:173], v[158:159], v[178:179]
	v_pk_fma_f32 v[116:117], v[218:219], v[152:153], v[116:117]
	v_pk_fma_f32 v[172:173], v[216:217], v[154:155], v[172:173]
	v_pk_fma_f32 v[106:107], v[148:149], v[106:107], v[116:117]
	v_pk_mul_f32 v[170:171], v[142:143], v[170:171]
	v_pk_mul_f32 v[104:105], v[140:141], v[104:105]
	v_pk_fma_f32 v[172:173], v[150:151], v[176:177], v[172:173]
	v_pk_add_f32 v[106:107], v[144:145], v[106:107]
	v_pk_fma_f32 v[170:171], v[180:181], v[134:135], v[170:171]
	v_pk_fma_f32 v[104:105], v[182:183], v[132:133], v[104:105]
	v_pk_add_f32 v[116:117], v[146:147], v[172:173]
	v_pk_fma_f32 v[104:105], v[128:129], v[118:119], v[104:105]
	v_pk_fma_f32 v[118:119], v[130:131], v[168:169], v[170:171]
	v_mul_f32_e32 v168, 0xbfb8aa3b, v106
	v_mul_f32_e32 v169, 0xbfb8aa3b, v107
	v_exp_f32_e32 v168, v168
	v_exp_f32_e32 v169, v169
	v_mul_f32_e32 v170, 0xbfb8aa3b, v116
	v_mul_f32_e32 v171, 0xbfb8aa3b, v117
	v_exp_f32_e32 v170, v170
	v_exp_f32_e32 v171, v171
	v_add_f32_e32 v168, 1.0, v168
	v_add_f32_e32 v169, 1.0, v169
	v_rcp_f32_e32 v168, v168
	v_rcp_f32_e32 v169, v169
	v_add_f32_e32 v170, 1.0, v170
	v_add_f32_e32 v171, 1.0, v171
	v_rcp_f32_e32 v170, v170
	v_rcp_f32_e32 v171, v171
	v_pk_add_f32 v[104:105], v[136:137], v[104:105]
	v_pk_mul_f32 v[106:107], v[106:107], v[168:169]
	v_pk_add_f32 v[118:119], v[138:139], v[118:119]
	v_pk_mul_f32 v[104:105], v[106:107], v[104:105]
	v_pk_mul_f32 v[106:107], v[116:117], v[170:171]
	v_cvt_pk_bf16_f32 v104, v104, v105
	v_pk_mul_f32 v[106:107], v[106:107], v[118:119]
	s_nop 0
	v_cvt_pk_bf16_f32 v105, v106, v107
	v_mov_b64_e32 v[106:107], s[52:53]
	v_mad_i64_i32 v[106:107], s[24:25], v199, s39, v[106:107]
	v_lshl_add_u64 v[106:107], v[196:197], 1, v[106:107]
	global_store_dwordx2 v[106:107], v[104:105], off
.LBB0_1465:
	s_or_b64 exec, exec, s[22:23]
	v_cndmask_b32_e64 v104, v114, v218, s[0:1]
	v_mov_b32_e32 v117, 0
	v_mov_b32_e32 v174, 0
	v_mov_b32_dpp v116, v104 row_ror:1 row_mask:0xf bank_mask:0xf
	v_cndmask_b32_e64 v104, v115, v219, s[0:1]
	v_mov_b32_e32 v175, 0
	v_mov_b32_e32 v106, 0
	v_mov_b32_dpp v117, v104 row_ror:1 row_mask:0xf bank_mask:0xf
	v_cndmask_b32_e64 v104, v108, v216, s[0:1]
	v_mov_b32_e32 v107, 0
	v_mov_b32_e32 v172, 0
	v_mov_b32_dpp v174, v104 row_ror:1 row_mask:0xf bank_mask:0xf
	v_cndmask_b32_e64 v104, v109, v217, s[0:1]
	v_mov_b32_e32 v173, 0
	v_cndmask_b32_e64 v105, v112, v182, s[0:1]
	v_mov_b32_dpp v175, v104 row_ror:1 row_mask:0xf bank_mask:0xf
	v_cndmask_b32_e64 v104, v114, v160, s[2:3]
	v_cndmask_b32_e64 v118, v113, v183, s[0:1]
	v_mov_b32_e32 v170, 0
	v_mov_b32_dpp v106, v104 row_ror:15 row_mask:0xf bank_mask:0xf
	v_cndmask_b32_e64 v104, v115, v161, s[2:3]
	v_mov_b32_e32 v171, 0
	v_cndmask_b32_e64 v119, v112, v164, s[2:3]
	v_mov_b32_dpp v107, v104 row_ror:15 row_mask:0xf bank_mask:0xf
	v_cndmask_b32_e64 v104, v108, v162, s[2:3]
	v_cndmask_b32_e64 v168, v113, v165, s[2:3]
	v_add_u32_e32 v176, s43, v228
	v_mov_b32_dpp v172, v104 row_ror:15 row_mask:0xf bank_mask:0xf
	v_cndmask_b32_e64 v104, v109, v163, s[2:3]
	v_cndmask_b32_e64 v169, v110, v166, s[2:3]
	v_cmp_gt_i32_e32 vcc, s42, v176
	v_mov_b32_dpp v173, v104 row_ror:15 row_mask:0xf bank_mask:0xf
	v_cndmask_b32_e64 v177, v111, v167, s[2:3]
	s_and_b64 s[96:97], s[66:67], vcc
	v_mov_b32_dpp v104, v105 row_ror:1 row_mask:0xf bank_mask:0xf
	s_nop 1
	v_mov_b32_dpp v105, v118 row_ror:1 row_mask:0xf bank_mask:0xf
	v_cndmask_b32_e64 v118, v110, v180, s[0:1]
	s_nop 1
	v_mov_b32_dpp v170, v118 row_ror:1 row_mask:0xf bank_mask:0xf
	v_cndmask_b32_e64 v118, v111, v181, s[0:1]
	s_nop 1
	v_mov_b32_dpp v171, v118 row_ror:1 row_mask:0xf bank_mask:0xf
	s_nop 1
	v_mov_b32_dpp v118, v119 row_ror:15 row_mask:0xf bank_mask:0xf
	s_nop 1
	v_mov_b32_dpp v119, v168 row_ror:15 row_mask:0xf bank_mask:0xf
	s_nop 1
	v_mov_b32_dpp v168, v169 row_ror:15 row_mask:0xf bank_mask:0xf
	s_nop 1
	v_mov_b32_dpp v169, v177 row_ror:15 row_mask:0xf bank_mask:0xf
	s_and_saveexec_b64 s[22:23], s[96:97]
	s_cbranch_execz .LBB0_1467
	v_pk_mul_f32 v[116:117], v[156:157], v[116:117]
	v_pk_mul_f32 v[174:175], v[158:159], v[174:175]
	v_pk_fma_f32 v[116:117], v[114:115], v[152:153], v[116:117]
	v_pk_fma_f32 v[174:175], v[108:109], v[154:155], v[174:175]
	v_pk_fma_f32 v[106:107], v[148:149], v[106:107], v[116:117]
	v_pk_mul_f32 v[170:171], v[142:143], v[170:171]
	v_pk_mul_f32 v[104:105], v[140:141], v[104:105]
	v_pk_fma_f32 v[172:173], v[150:151], v[172:173], v[174:175]
	v_pk_add_f32 v[106:107], v[144:145], v[106:107]
	v_pk_fma_f32 v[170:171], v[110:111], v[134:135], v[170:171]
	v_pk_fma_f32 v[104:105], v[112:113], v[132:133], v[104:105]
	v_pk_add_f32 v[116:117], v[146:147], v[172:173]
	v_pk_fma_f32 v[104:105], v[128:129], v[118:119], v[104:105]
	v_pk_fma_f32 v[118:119], v[130:131], v[168:169], v[170:171]
	v_mul_f32_e32 v168, 0xbfb8aa3b, v106
	v_mul_f32_e32 v169, 0xbfb8aa3b, v107
	v_exp_f32_e32 v168, v168
	v_exp_f32_e32 v169, v169
	v_mul_f32_e32 v170, 0xbfb8aa3b, v116
	v_mul_f32_e32 v171, 0xbfb8aa3b, v117
	v_exp_f32_e32 v170, v170
	v_exp_f32_e32 v171, v171
	v_add_f32_e32 v168, 1.0, v168
	v_add_f32_e32 v169, 1.0, v169
	v_rcp_f32_e32 v168, v168
	v_rcp_f32_e32 v169, v169
	v_add_f32_e32 v170, 1.0, v170
	v_add_f32_e32 v171, 1.0, v171
	v_rcp_f32_e32 v170, v170
	v_rcp_f32_e32 v171, v171
	v_pk_add_f32 v[104:105], v[136:137], v[104:105]
	v_pk_mul_f32 v[106:107], v[106:107], v[168:169]
	v_pk_add_f32 v[118:119], v[138:139], v[118:119]
	v_pk_mul_f32 v[104:105], v[106:107], v[104:105]
	v_pk_mul_f32 v[106:107], v[116:117], v[170:171]
	v_cvt_pk_bf16_f32 v104, v104, v105
	v_pk_mul_f32 v[106:107], v[106:107], v[118:119]
	s_nop 0
	v_cvt_pk_bf16_f32 v105, v106, v107
	v_mov_b64_e32 v[106:107], s[52:53]
	v_mad_i64_i32 v[106:107], s[24:25], v176, s39, v[106:107]
	v_lshl_add_u64 v[106:107], v[196:197], 1, v[106:107]
	global_store_dwordx2 v[106:107], v[104:105], off
.LBB0_1467:
	s_or_b64 exec, exec, s[22:23]
	v_cndmask_b32_e64 v104, v160, v114, s[0:1]
	v_mov_b32_e32 v116, 0
	v_readlane_b32 s24, v253, 60
	v_mov_b32_dpp v114, v104 row_ror:1 row_mask:0xf bank_mask:0xf
	v_cndmask_b32_e64 v104, v161, v115, s[0:1]
	v_mov_b32_e32 v117, 0
	v_readlane_b32 s25, v253, 61
	v_mov_b32_dpp v115, v104 row_ror:1 row_mask:0xf bank_mask:0xf
	v_cndmask_b32_e64 v104, v162, v108, s[0:1]
	v_mov_b32_e32 v108, 0
	s_andn2_b64 vcc, exec, s[24:25]
	v_mov_b32_dpp v116, v104 row_ror:1 row_mask:0xf bank_mask:0xf
	v_cndmask_b32_e64 v104, v163, v109, s[0:1]
	v_lshl_add_u32 v168, v223, 2, s9
	v_mov_b32_e32 v105, 0
	v_mov_b32_dpp v117, v104 row_ror:1 row_mask:0xf bank_mask:0xf
	v_cndmask_b32_e64 v104, 0, 1, s[24:25]
	v_cmp_ne_u32_e64 s[22:23], 1, v104
	v_mov_b32_e32 v104, 0
	v_mov_b32_e32 v106, 0
	v_mov_b32_e32 v107, 0
	s_cbranch_vccnz .LBB0_1469
	ds_read_b128 v[104:107], v168 offset:2048
.LBB0_1469:
	v_cndmask_b32_e64 v109, v164, v112, s[0:1]
	v_mov_b32_e32 v118, 0
	v_mov_b32_e32 v169, 0
	v_mov_b32_dpp v112, v109 row_ror:1 row_mask:0xf bank_mask:0xf
	v_cndmask_b32_e64 v109, v165, v113, s[0:1]
	v_mov_b32_e32 v170, 0
	v_mov_b32_e32 v171, 0
	v_mov_b32_dpp v113, v109 row_ror:1 row_mask:0xf bank_mask:0xf
	v_cndmask_b32_e64 v109, v166, v110, s[0:1]
	v_mov_b32_e32 v172, 0
	v_mov_b32_e32 v119, 0
	v_mov_b32_dpp v118, v109 row_ror:1 row_mask:0xf bank_mask:0xf
	v_cndmask_b32_e64 v109, v167, v111, s[0:1]
	v_mov_b32_dpp v169, v160 row_ror:15 row_mask:0xf bank_mask:0xf
	v_mov_b32_dpp v170, v161 row_ror:15 row_mask:0xf bank_mask:0xf
	v_mov_b32_dpp v171, v162 row_ror:15 row_mask:0xf bank_mask:0xf
	v_mov_b32_dpp v172, v163 row_ror:15 row_mask:0xf bank_mask:0xf
	v_mov_b32_dpp v119, v109 row_ror:1 row_mask:0xf bank_mask:0xf
	s_and_b64 vcc, exec, s[22:23]
	v_mov_b32_e32 v109, 0
	v_mov_b32_e32 v110, 0
	v_mov_b32_e32 v111, 0
	s_cbranch_vccnz .LBB0_1471
	ds_read_b128 v[108:111], v168 offset:2560
.LBB0_1471:
	v_pk_mul_f32 v[114:115], v[156:157], v[114:115]
	s_waitcnt lgkmcnt(0)
	v_cndmask_b32_e64 v104, v169, v104, s[0:1]
	v_cndmask_b32_e64 v105, v170, v105, s[0:1]
	v_pk_mul_f32 v[116:117], v[158:159], v[116:117]
	v_pk_fma_f32 v[114:115], v[160:161], v[152:153], v[114:115]
	v_cndmask_b32_e64 v106, v171, v106, s[0:1]
	v_cndmask_b32_e64 v107, v172, v107, s[0:1]
	v_pk_fma_f32 v[116:117], v[162:163], v[154:155], v[116:117]
	v_pk_fma_f32 v[104:105], v[148:149], v[104:105], v[114:115]
	v_pk_fma_f32 v[106:107], v[150:151], v[106:107], v[116:117]
	v_mov_b32_dpp v114, v164 row_ror:15 row_mask:0xf bank_mask:0xf
	v_mov_b32_dpp v115, v165 row_ror:15 row_mask:0xf bank_mask:0xf
	v_add_u32_e32 v169, s43, v229
	v_mov_b32_dpp v116, v166 row_ror:15 row_mask:0xf bank_mask:0xf
	v_mov_b32_dpp v117, v167 row_ror:15 row_mask:0xf bank_mask:0xf
	v_cndmask_b32_e64 v108, v114, v108, s[0:1]
	v_cndmask_b32_e64 v109, v115, v109, s[0:1]
	v_pk_mul_f32 v[114:115], v[142:143], v[118:119]
	v_pk_mul_f32 v[112:113], v[140:141], v[112:113]
	v_readlane_b32 s26, v252, 0
	v_cmp_le_i32_e32 vcc, s42, v169
	v_cndmask_b32_e64 v110, v116, v110, s[0:1]
	v_cndmask_b32_e64 v111, v117, v111, s[0:1]
	v_pk_fma_f32 v[114:115], v[166:167], v[134:135], v[114:115]
	v_pk_fma_f32 v[112:113], v[164:165], v[132:133], v[112:113]
	v_readlane_b32 s27, v252, 1
	v_pk_fma_f32 v[110:111], v[130:131], v[110:111], v[114:115]
	v_pk_fma_f32 v[108:109], v[128:129], v[108:109], v[112:113]
	s_or_b64 s[24:25], s[62:63], vcc
	s_and_b64 s[90:91], s[26:27], s[88:89]
	v_pk_add_f32 v[104:105], v[144:145], v[104:105]
	v_pk_add_f32 v[106:107], v[146:147], v[106:107]
	v_pk_add_f32 v[110:111], v[138:139], v[110:111]
	v_pk_add_f32 v[108:109], v[136:137], v[108:109]
	s_nor_b64 s[84:85], s[24:25], s[90:91]
	s_and_saveexec_b64 s[24:25], s[84:85]
	s_cbranch_execz .LBB0_1473
	v_mul_f32_e32 v112, 0xbfb8aa3b, v104
	v_mul_f32_e32 v113, 0xbfb8aa3b, v105
	v_mul_f32_e32 v114, 0xbfb8aa3b, v106
	v_mul_f32_e32 v115, 0xbfb8aa3b, v107
	v_exp_f32_e32 v112, v112
	v_exp_f32_e32 v113, v113
	v_exp_f32_e32 v114, v114
	v_exp_f32_e32 v115, v115
	v_add_f32_e32 v112, 1.0, v112
	v_add_f32_e32 v113, 1.0, v113
	v_add_f32_e32 v114, 1.0, v114
	v_add_f32_e32 v115, 1.0, v115
	v_rcp_f32_e32 v112, v112
	v_rcp_f32_e32 v113, v113
	v_rcp_f32_e32 v114, v114
	v_rcp_f32_e32 v115, v115
	v_pk_mul_f32 v[112:113], v[104:105], v[112:113]
	s_nop 0
	v_pk_mul_f32 v[112:113], v[112:113], v[108:109]
	v_pk_mul_f32 v[114:115], v[106:107], v[114:115]
	v_cvt_pk_bf16_f32 v112, v112, v113
	v_pk_mul_f32 v[114:115], v[114:115], v[110:111]
	s_nop 0
	v_cvt_pk_bf16_f32 v113, v114, v115
	v_mov_b64_e32 v[114:115], s[52:53]
	v_mad_i64_i32 v[114:115], s[26:27], v169, s39, v[114:115]
	v_lshl_add_u64 v[114:115], v[196:197], 1, v[114:115]
	global_store_dwordx2 v[114:115], v[112:113], off

.LBB0_1475:
	s_or_b64 exec, exec, s[24:25]
	v_pk_fma_f32 v[78:79], v[78:79], v[200:201], v[98:99] op_sel_hi:[1,0,1]
	v_pk_fma_f32 v[104:105], v[76:77], v[200:201], v[96:97] op_sel_hi:[1,0,1]
	v_cndmask_b32_e64 v77, 0, v79, s[14:15]
	v_cndmask_b32_e64 v76, 0, v78, s[14:15]
	v_cndmask_b32_e64 v79, 0, v105, s[14:15]
	v_cndmask_b32_e64 v78, 0, v104, s[14:15]
	v_pk_fma_f32 v[74:75], v[74:75], v[200:201], v[102:103] op_sel_hi:[1,0,1]
	v_pk_fma_f32 v[104:105], v[72:73], v[200:201], v[100:101] op_sel_hi:[1,0,1]
	v_cndmask_b32_e64 v73, 0, v75, s[14:15]
	v_cndmask_b32_e64 v72, 0, v74, s[14:15]
	v_cndmask_b32_e64 v75, 0, v105, s[14:15]
	v_cndmask_b32_e64 v74, 0, v104, s[14:15]
	v_cndmask_b32_e64 v105, v124, v78, s[2:3]
	v_cndmask_b32_e64 v106, v125, v79, s[2:3]
	v_cndmask_b32_e64 v107, v126, v76, s[2:3]
	v_mov_b32_dpp v104, v105 row_ror:15 row_mask:0xf bank_mask:0xf
	v_cndmask_b32_e64 v108, v127, v77, s[2:3]
	v_cndmask_b32_e64 v109, v120, v74, s[2:3]
	v_mov_b32_dpp v105, v106 row_ror:15 row_mask:0xf bank_mask:0xf
	v_cndmask_b32_e64 v110, v121, v75, s[2:3]
	v_readlane_b32 s24, v253, 26
	v_mov_b32_dpp v106, v107 row_ror:15 row_mask:0xf bank_mask:0xf
	v_add_u32_e32 v160, s43, v230
	v_cndmask_b32_e64 v111, v122, v72, s[2:3]
	v_mov_b32_dpp v107, v108 row_ror:15 row_mask:0xf bank_mask:0xf
	v_readlane_b32 s25, v253, 27
	v_cmp_gt_i32_e32 vcc, s42, v160
	v_mov_b32_dpp v108, v109 row_ror:15 row_mask:0xf bank_mask:0xf
	v_mov_b32_dpp v109, v110 row_ror:15 row_mask:0xf bank_mask:0xf
	v_mov_b32_dpp v110, v111 row_ror:15 row_mask:0xf bank_mask:0xf
	v_cndmask_b32_e64 v161, v123, v73, s[2:3]
	s_xor_b64 s[24:25], s[24:25], -1
	v_mov_b32_dpp v112, v124 row_ror:1 row_mask:0xf bank_mask:0xf
	v_mov_b32_dpp v113, v125 row_ror:1 row_mask:0xf bank_mask:0xf
	v_mov_b32_dpp v114, v126 row_ror:1 row_mask:0xf bank_mask:0xf
	v_mov_b32_dpp v115, v127 row_ror:1 row_mask:0xf bank_mask:0xf
	v_mov_b32_dpp v116, v120 row_ror:1 row_mask:0xf bank_mask:0xf
	v_mov_b32_dpp v117, v121 row_ror:1 row_mask:0xf bank_mask:0xf
	v_mov_b32_dpp v118, v122 row_ror:1 row_mask:0xf bank_mask:0xf
	v_mov_b32_dpp v119, v123 row_ror:1 row_mask:0xf bank_mask:0xf
	v_mov_b32_dpp v111, v161 row_ror:15 row_mask:0xf bank_mask:0xf
	s_and_b64 s[34:35], s[24:25], vcc
	s_and_saveexec_b64 s[26:27], s[34:35]
	s_cbranch_execz .LBB0_1477
	ds_read_b128 v[162:165], v168 offset:3584
	s_waitcnt lgkmcnt(0)
	v_cndmask_b32_e64 v116, v116, v162, s[2:3]
	v_cndmask_b32_e64 v117, v117, v163, s[2:3]
	v_cndmask_b32_e64 v118, v118, v164, s[2:3]
	v_cndmask_b32_e64 v119, v119, v165, s[2:3]
	v_pk_mul_f32 v[116:117], v[140:141], v[116:117]
	v_pk_mul_f32 v[118:119], v[142:143], v[118:119]
	v_pk_fma_f32 v[116:117], v[120:121], v[132:133], v[116:117]
	v_pk_fma_f32 v[118:119], v[122:123], v[134:135], v[118:119]
	v_pk_fma_f32 v[108:109], v[128:129], v[108:109], v[116:117]
	v_pk_fma_f32 v[110:111], v[130:131], v[110:111], v[118:119]
	v_pk_add_f32 v[118:119], v[136:137], v[108:109]
	v_pk_add_f32 v[116:117], v[138:139], v[110:111]
	ds_read_b128 v[108:111], v168 offset:3072
	s_waitcnt lgkmcnt(0)
	v_cndmask_b32_e64 v108, v112, v108, s[2:3]
	v_cndmask_b32_e64 v109, v113, v109, s[2:3]
	v_pk_mul_f32 v[108:109], v[156:157], v[108:109]
	v_cndmask_b32_e64 v110, v114, v110, s[2:3]
	v_pk_fma_f32 v[108:109], v[124:125], v[152:153], v[108:109]
	v_cndmask_b32_e64 v111, v115, v111, s[2:3]
	v_pk_fma_f32 v[104:105], v[148:149], v[104:105], v[108:109]
	v_pk_mul_f32 v[110:111], v[158:159], v[110:111]
	v_pk_add_f32 v[104:105], v[144:145], v[104:105]
	v_pk_fma_f32 v[110:111], v[126:127], v[154:155], v[110:111]
	v_mul_f32_e32 v108, 0xbfb8aa3b, v104
	v_mul_f32_e32 v109, 0xbfb8aa3b, v105
	v_exp_f32_e32 v108, v108
	v_exp_f32_e32 v109, v109
	v_pk_fma_f32 v[106:107], v[150:151], v[106:107], v[110:111]
	v_add_f32_e32 v108, 1.0, v108
	v_add_f32_e32 v109, 1.0, v109
	v_rcp_f32_e32 v108, v108
	v_rcp_f32_e32 v109, v109
	v_pk_add_f32 v[106:107], v[146:147], v[106:107]
	v_pk_mul_f32 v[104:105], v[104:105], v[108:109]
	v_mul_f32_e32 v108, 0xbfb8aa3b, v106
	v_mul_f32_e32 v109, 0xbfb8aa3b, v107
	v_exp_f32_e32 v108, v108
	v_exp_f32_e32 v109, v109
	v_pk_mul_f32 v[104:105], v[118:119], v[104:105]
	v_add_f32_e32 v108, 1.0, v108
	v_add_f32_e32 v109, 1.0, v109
	v_rcp_f32_e32 v108, v108
	v_rcp_f32_e32 v109, v109
	v_cvt_pk_bf16_f32 v104, v104, v105
	v_pk_mul_f32 v[106:107], v[106:107], v[108:109]
	s_nop 0
	v_pk_mul_f32 v[106:107], v[116:117], v[106:107]
	s_nop 0
	v_cvt_pk_bf16_f32 v105, v106, v107
	v_mov_b64_e32 v[106:107], s[52:53]
	v_mad_i64_i32 v[106:107], s[36:37], v160, s39, v[106:107]
	v_lshl_add_u64 v[106:107], v[196:197], 1, v[106:107]
	global_store_dwordx2 v[106:107], v[104:105], off
.LBB0_1477:
	s_or_b64 exec, exec, s[26:27]
	v_pk_fma_f32 v[96:97], v[68:69], v[198:199], v[96:97] op_sel_hi:[1,0,1]
	v_pk_fma_f32 v[64:65], v[64:65], v[198:199], v[100:101] op_sel_hi:[1,0,1]
	v_pk_fma_f32 v[70:71], v[70:71], v[198:199], v[98:99] op_sel_hi:[1,0,1]
	v_cndmask_b32_e64 v98, 0, v96, s[12:13]
	v_cndmask_b32_e64 v96, 0, v64, s[12:13]
	v_cndmask_b32_e64 v64, v78, v124, s[0:1]
	v_mov_b32_e32 v101, 0
	v_mov_b32_e32 v110, 0
	v_mov_b32_dpp v100, v64 row_ror:1 row_mask:0xf bank_mask:0xf
	v_cndmask_b32_e64 v64, v79, v125, s[0:1]
	v_pk_fma_f32 v[66:67], v[66:67], v[198:199], v[102:103] op_sel_hi:[1,0,1]
	v_mov_b32_e32 v111, 0
	v_mov_b32_dpp v101, v64 row_ror:1 row_mask:0xf bank_mask:0xf
	v_cndmask_b32_e64 v64, v76, v126, s[0:1]
	v_cndmask_b32_e64 v68, 0, v70, s[12:13]
	v_cndmask_b32_e64 v99, 0, v97, s[12:13]
	v_mov_b32_dpp v110, v64 row_ror:1 row_mask:0xf bank_mask:0xf
	v_cndmask_b32_e64 v64, v77, v127, s[0:1]
	v_cndmask_b32_e64 v70, 0, v66, s[12:13]
	v_mov_b32_e32 v66, 0
	v_mov_b32_dpp v111, v64 row_ror:1 row_mask:0xf bank_mask:0xf
	v_cndmask_b32_e64 v64, v78, v98, s[2:3]
	v_cndmask_b32_e64 v69, 0, v71, s[12:13]
	v_cndmask_b32_e64 v71, 0, v67, s[12:13]
	v_mov_b32_dpp v66, v64 row_ror:15 row_mask:0xf bank_mask:0xf
	v_cndmask_b32_e64 v64, v79, v99, s[2:3]
	v_mov_b32_e32 v108, 0
	v_mov_b32_e32 v109, 0
	v_mov_b32_dpp v67, v64 row_ror:15 row_mask:0xf bank_mask:0xf
	v_cndmask_b32_e64 v64, v76, v68, s[2:3]
	v_cndmask_b32_e64 v97, 0, v65, s[12:13]
	v_cndmask_b32_e64 v65, v74, v120, s[0:1]
	v_mov_b32_dpp v108, v64 row_ror:15 row_mask:0xf bank_mask:0xf
	v_cndmask_b32_e64 v64, v77, v69, s[2:3]
	v_cndmask_b32_e64 v102, v75, v121, s[0:1]
	v_mov_b32_e32 v106, 0
	v_mov_b32_dpp v109, v64 row_ror:15 row_mask:0xf bank_mask:0xf
	v_cndmask_b32_e64 v103, v74, v96, s[2:3]
	v_mov_b32_dpp v64, v65 row_ror:1 row_mask:0xf bank_mask:0xf
	v_cndmask_b32_e64 v104, v75, v97, s[2:3]
	v_add_u32_e32 v161, s43, v231
	v_mov_b32_dpp v65, v102 row_ror:1 row_mask:0xf bank_mask:0xf
	v_cndmask_b32_e64 v102, v72, v122, s[0:1]
	v_cndmask_b32_e64 v105, v72, v70, s[2:3]
	v_cmp_gt_i32_e32 vcc, s42, v161
	v_mov_b32_dpp v106, v102 row_ror:1 row_mask:0xf bank_mask:0xf
	v_cndmask_b32_e64 v102, v73, v123, s[0:1]
	v_cndmask_b32_e64 v112, v73, v71, s[2:3]
	s_and_b64 s[36:37], s[24:25], vcc
	v_mov_b32_dpp v107, v102 row_ror:1 row_mask:0xf bank_mask:0xf
	s_nop 1
	v_mov_b32_dpp v102, v103 row_ror:15 row_mask:0xf bank_mask:0xf
	s_nop 1
	v_mov_b32_dpp v103, v104 row_ror:15 row_mask:0xf bank_mask:0xf
	s_nop 1
	v_mov_b32_dpp v104, v105 row_ror:15 row_mask:0xf bank_mask:0xf
	s_nop 1
	v_mov_b32_dpp v105, v112 row_ror:15 row_mask:0xf bank_mask:0xf
	s_and_saveexec_b64 s[26:27], s[36:37]
	s_cbranch_execz .LBB0_1479
	v_pk_mul_f32 v[100:101], v[156:157], v[100:101]
	v_pk_mul_f32 v[110:111], v[158:159], v[110:111]
	v_pk_fma_f32 v[100:101], v[78:79], v[152:153], v[100:101]
	v_pk_fma_f32 v[110:111], v[76:77], v[154:155], v[110:111]
	v_pk_fma_f32 v[66:67], v[148:149], v[66:67], v[100:101]
	v_pk_mul_f32 v[106:107], v[142:143], v[106:107]
	v_pk_mul_f32 v[64:65], v[140:141], v[64:65]
	v_pk_fma_f32 v[108:109], v[150:151], v[108:109], v[110:111]
	v_pk_add_f32 v[66:67], v[144:145], v[66:67]
	v_pk_fma_f32 v[106:107], v[72:73], v[134:135], v[106:107]
	v_pk_fma_f32 v[64:65], v[74:75], v[132:133], v[64:65]
	v_pk_add_f32 v[100:101], v[146:147], v[108:109]
	v_pk_fma_f32 v[64:65], v[128:129], v[102:103], v[64:65]
	v_pk_fma_f32 v[102:103], v[130:131], v[104:105], v[106:107]
	v_mul_f32_e32 v104, 0xbfb8aa3b, v66
	v_mul_f32_e32 v105, 0xbfb8aa3b, v67
	v_exp_f32_e32 v104, v104
	v_exp_f32_e32 v105, v105
	v_mul_f32_e32 v106, 0xbfb8aa3b, v100
	v_mul_f32_e32 v107, 0xbfb8aa3b, v101
	v_exp_f32_e32 v106, v106
	v_exp_f32_e32 v107, v107
	v_add_f32_e32 v104, 1.0, v104
	v_add_f32_e32 v105, 1.0, v105
	v_rcp_f32_e32 v104, v104
	v_rcp_f32_e32 v105, v105
	v_add_f32_e32 v106, 1.0, v106
	v_add_f32_e32 v107, 1.0, v107
	v_rcp_f32_e32 v106, v106
	v_rcp_f32_e32 v107, v107
	v_pk_add_f32 v[64:65], v[136:137], v[64:65]
	v_pk_mul_f32 v[66:67], v[66:67], v[104:105]
	v_pk_add_f32 v[102:103], v[138:139], v[102:103]
	v_pk_mul_f32 v[64:65], v[66:67], v[64:65]
	v_pk_mul_f32 v[66:67], v[100:101], v[106:107]
	v_cvt_pk_bf16_f32 v64, v64, v65
	v_pk_mul_f32 v[66:67], v[66:67], v[102:103]
	s_nop 0
	v_cvt_pk_bf16_f32 v65, v66, v67
	v_mov_b64_e32 v[66:67], s[52:53]
	v_mad_i64_i32 v[66:67], s[40:41], v161, s39, v[66:67]
	v_lshl_add_u64 v[66:67], v[196:197], 1, v[66:67]
	global_store_dwordx2 v[66:67], v[64:65], off
.LBB0_1479:
	s_or_b64 exec, exec, s[26:27]
	v_cndmask_b32_e64 v64, v98, v78, s[0:1]
	v_mov_b32_e32 v102, 0
	v_mov_b32_e32 v103, 0
	v_mov_b32_dpp v78, v64 row_ror:1 row_mask:0xf bank_mask:0xf
	v_cndmask_b32_e64 v64, v99, v79, s[0:1]
	v_mov_b32_e32 v66, 0
	v_mov_b32_e32 v67, 0
	v_mov_b32_dpp v79, v64 row_ror:1 row_mask:0xf bank_mask:0xf
	v_cndmask_b32_e64 v64, v68, v76, s[0:1]
	v_mov_b32_e32 v100, 0
	v_mov_b32_e32 v101, 0
	v_mov_b32_dpp v102, v64 row_ror:1 row_mask:0xf bank_mask:0xf
	v_cndmask_b32_e64 v64, v69, v77, s[0:1]
	v_cndmask_b32_e64 v72, v70, v72, s[0:1]
	v_mov_b32_e32 v76, 0
	v_mov_b32_dpp v103, v64 row_ror:1 row_mask:0xf bank_mask:0xf
	v_cndmask_b32_e64 v64, v98, v88, s[2:3]
	v_cndmask_b32_e64 v65, v96, v74, s[0:1]
	v_mov_b32_dpp v76, v72 row_ror:1 row_mask:0xf bank_mask:0xf
	v_mov_b32_dpp v66, v64 row_ror:15 row_mask:0xf bank_mask:0xf
	v_cndmask_b32_e64 v64, v99, v89, s[2:3]
	v_cndmask_b32_e64 v72, v71, v73, s[0:1]
	v_mov_b32_e32 v77, 0
	v_mov_b32_dpp v67, v64 row_ror:15 row_mask:0xf bank_mask:0xf
	v_cndmask_b32_e64 v64, v68, v90, s[2:3]
	v_cndmask_b32_e64 v74, v97, v75, s[0:1]
	v_mov_b32_dpp v77, v72 row_ror:1 row_mask:0xf bank_mask:0xf
	v_mov_b32_dpp v100, v64 row_ror:15 row_mask:0xf bank_mask:0xf
	v_cndmask_b32_e64 v64, v69, v91, s[2:3]
	v_cndmask_b32_e64 v73, v96, v92, s[2:3]
	v_mov_b32_e32 v72, 0
	v_mov_b32_dpp v101, v64 row_ror:15 row_mask:0xf bank_mask:0xf
	v_mov_b32_e32 v64, 0
	v_mov_b32_dpp v72, v73 row_ror:15 row_mask:0xf bank_mask:0xf
	v_mov_b32_dpp v64, v65 row_ror:1 row_mask:0xf bank_mask:0xf
	v_add_u32_e32 v120, s43, v232
	v_cndmask_b32_e64 v75, v70, v94, s[2:3]
	v_mov_b32_dpp v65, v74 row_ror:1 row_mask:0xf bank_mask:0xf
	v_cndmask_b32_e64 v74, v97, v93, s[2:3]
	v_cmp_gt_i32_e32 vcc, s42, v120
	v_cndmask_b32_e64 v104, v71, v95, s[2:3]
	v_mov_b32_dpp v73, v74 row_ror:15 row_mask:0xf bank_mask:0xf
	s_and_b64 s[40:41], s[24:25], vcc
	s_nop 0
	v_mov_b32_dpp v74, v75 row_ror:15 row_mask:0xf bank_mask:0xf
	s_nop 1
	v_mov_b32_dpp v75, v104 row_ror:15 row_mask:0xf bank_mask:0xf
	s_and_saveexec_b64 s[24:25], s[40:41]
	s_cbranch_execz .LBB0_1481
	v_pk_mul_f32 v[78:79], v[156:157], v[78:79]
	v_pk_mul_f32 v[102:103], v[158:159], v[102:103]
	v_pk_fma_f32 v[78:79], v[98:99], v[152:153], v[78:79]
	v_pk_fma_f32 v[102:103], v[68:69], v[154:155], v[102:103]
	v_pk_fma_f32 v[66:67], v[148:149], v[66:67], v[78:79]
	v_pk_mul_f32 v[76:77], v[142:143], v[76:77]
	v_pk_mul_f32 v[64:65], v[140:141], v[64:65]
	v_pk_fma_f32 v[100:101], v[150:151], v[100:101], v[102:103]
	v_pk_add_f32 v[66:67], v[144:145], v[66:67]
	v_pk_fma_f32 v[76:77], v[70:71], v[134:135], v[76:77]
	v_pk_fma_f32 v[64:65], v[96:97], v[132:133], v[64:65]
	v_pk_add_f32 v[78:79], v[146:147], v[100:101]
	v_pk_fma_f32 v[64:65], v[128:129], v[72:73], v[64:65]
	v_pk_fma_f32 v[72:73], v[130:131], v[74:75], v[76:77]
	v_mul_f32_e32 v74, 0xbfb8aa3b, v66
	v_mul_f32_e32 v75, 0xbfb8aa3b, v67
	v_exp_f32_e32 v74, v74
	v_exp_f32_e32 v75, v75
	v_mul_f32_e32 v76, 0xbfb8aa3b, v78
	v_mul_f32_e32 v77, 0xbfb8aa3b, v79
	v_exp_f32_e32 v76, v76
	v_exp_f32_e32 v77, v77
	v_add_f32_e32 v74, 1.0, v74
	v_add_f32_e32 v75, 1.0, v75
	v_rcp_f32_e32 v74, v74
	v_rcp_f32_e32 v75, v75
	v_add_f32_e32 v76, 1.0, v76
	v_add_f32_e32 v77, 1.0, v77
	v_rcp_f32_e32 v76, v76
	v_rcp_f32_e32 v77, v77
	v_pk_add_f32 v[64:65], v[136:137], v[64:65]
	v_pk_mul_f32 v[66:67], v[66:67], v[74:75]
	v_pk_add_f32 v[72:73], v[138:139], v[72:73]
	v_pk_mul_f32 v[64:65], v[66:67], v[64:65]
	v_pk_mul_f32 v[66:67], v[78:79], v[76:77]
	v_cvt_pk_bf16_f32 v64, v64, v65
	v_pk_mul_f32 v[66:67], v[66:67], v[72:73]
	s_nop 0
	v_cvt_pk_bf16_f32 v65, v66, v67
	v_mov_b64_e32 v[66:67], s[52:53]
	v_mad_i64_i32 v[66:67], s[26:27], v120, s39, v[66:67]
	v_lshl_add_u64 v[66:67], v[196:197], 1, v[66:67]
	global_store_dwordx2 v[66:67], v[64:65], off
.LBB0_1481:
	s_or_b64 exec, exec, s[24:25]
	v_cndmask_b32_e64 v64, v88, v98, s[0:1]
	v_mov_b32_e32 v75, 0
	v_mov_b32_e32 v78, 0
	v_mov_b32_dpp v74, v64 row_ror:1 row_mask:0xf bank_mask:0xf
	v_cndmask_b32_e64 v64, v89, v99, s[0:1]
	v_mov_b32_e32 v79, 0
	s_andn2_b64 vcc, exec, s[82:83]
	v_mov_b32_dpp v75, v64 row_ror:1 row_mask:0xf bank_mask:0xf
	v_cndmask_b32_e64 v64, v90, v68, s[0:1]
	v_mov_b32_e32 v68, 0
	v_mov_b32_e32 v65, 0
	v_mov_b32_dpp v78, v64 row_ror:1 row_mask:0xf bank_mask:0xf
	v_cndmask_b32_e64 v64, v91, v69, s[0:1]
	v_mov_b32_e32 v66, 0
	v_mov_b32_e32 v67, 0
	v_mov_b32_dpp v79, v64 row_ror:1 row_mask:0xf bank_mask:0xf
	v_cndmask_b32_e64 v64, 0, 1, s[82:83]
	v_cmp_ne_u32_e64 s[24:25], 1, v64
	v_mov_b32_e32 v64, 0
	s_cbranch_vccnz .LBB0_1483
	ds_read_b128 v[64:67], v168 offset:6144
.LBB0_1483:
	v_cndmask_b32_e64 v69, v92, v96, s[0:1]
	v_mov_b32_e32 v73, 0
	v_mov_b32_e32 v76, 0
	v_mov_b32_dpp v72, v69 row_ror:1 row_mask:0xf bank_mask:0xf
	v_cndmask_b32_e64 v69, v93, v97, s[0:1]
	v_mov_b32_e32 v98, 0
	v_mov_b32_e32 v99, 0
	v_mov_b32_dpp v73, v69 row_ror:1 row_mask:0xf bank_mask:0xf
	v_cndmask_b32_e64 v69, v94, v70, s[0:1]
	v_mov_b32_e32 v100, 0
	v_mov_b32_e32 v101, 0
	v_mov_b32_dpp v76, v69 row_ror:1 row_mask:0xf bank_mask:0xf
	v_cndmask_b32_e64 v69, v95, v71, s[0:1]
	v_mov_b32_dpp v98, v88 row_ror:15 row_mask:0xf bank_mask:0xf
	v_mov_b32_dpp v99, v89 row_ror:15 row_mask:0xf bank_mask:0xf
	v_mov_b32_dpp v100, v90 row_ror:15 row_mask:0xf bank_mask:0xf
	v_mov_b32_dpp v101, v91 row_ror:15 row_mask:0xf bank_mask:0xf
	v_mov_b32_dpp v77, v69 row_ror:1 row_mask:0xf bank_mask:0xf
	s_and_b64 vcc, exec, s[24:25]
	v_mov_b32_e32 v69, 0
	v_mov_b32_e32 v70, 0
	v_mov_b32_e32 v71, 0
	s_cbranch_vccnz .LBB0_1485
	ds_read_b128 v[68:71], v168 offset:6656
.LBB0_1485:
	v_pk_mul_f32 v[74:75], v[156:157], v[74:75]
	s_waitcnt lgkmcnt(0)
	v_cndmask_b32_e64 v64, v98, v64, s[0:1]
	v_cndmask_b32_e64 v65, v99, v65, s[0:1]
	v_pk_mul_f32 v[78:79], v[158:159], v[78:79]
	v_pk_fma_f32 v[74:75], v[88:89], v[152:153], v[74:75]
	v_cndmask_b32_e64 v66, v100, v66, s[0:1]
	v_cndmask_b32_e64 v67, v101, v67, s[0:1]
	v_pk_fma_f32 v[78:79], v[90:91], v[154:155], v[78:79]
	v_pk_fma_f32 v[64:65], v[148:149], v[64:65], v[74:75]
	v_pk_fma_f32 v[66:67], v[150:151], v[66:67], v[78:79]
	v_add_u32_e32 v121, s43, v233
	v_mov_b32_dpp v74, v92 row_ror:15 row_mask:0xf bank_mask:0xf
	v_mov_b32_dpp v75, v93 row_ror:15 row_mask:0xf bank_mask:0xf
	v_cmp_le_i32_e32 vcc, s42, v121
	v_mov_b32_dpp v78, v94 row_ror:15 row_mask:0xf bank_mask:0xf
	v_mov_b32_dpp v79, v95 row_ror:15 row_mask:0xf bank_mask:0xf
	v_cndmask_b32_e64 v68, v74, v68, s[0:1]
	v_cndmask_b32_e64 v69, v75, v69, s[0:1]
	v_pk_mul_f32 v[74:75], v[142:143], v[76:77]
	v_pk_mul_f32 v[72:73], v[140:141], v[72:73]
	v_readlane_b32 s26, v253, 26
	v_readlane_b32 s42, v252, 2
	v_cndmask_b32_e64 v70, v78, v70, s[0:1]
	v_cndmask_b32_e64 v71, v79, v71, s[0:1]
	v_pk_fma_f32 v[74:75], v[94:95], v[134:135], v[74:75]
	v_pk_fma_f32 v[72:73], v[92:93], v[132:133], v[72:73]
	v_readlane_b32 s27, v253, 27
	v_readlane_b32 s43, v252, 3
	v_pk_fma_f32 v[70:71], v[130:131], v[70:71], v[74:75]
	v_pk_fma_f32 v[68:69], v[128:129], v[68:69], v[72:73]
	s_or_b64 s[26:27], s[26:27], vcc
	s_and_b64 s[88:89], s[42:43], s[88:89]
	v_pk_add_f32 v[64:65], v[144:145], v[64:65]
	v_pk_add_f32 v[66:67], v[146:147], v[66:67]
	v_pk_add_f32 v[70:71], v[138:139], v[70:71]
	v_pk_add_f32 v[68:69], v[136:137], v[68:69]
	s_nor_b64 s[26:27], s[26:27], s[88:89]
	s_and_saveexec_b64 vcc, s[26:27]
	s_cbranch_execz .LBB0_1487
	v_mul_f32_e32 v72, 0xbfb8aa3b, v64
	v_mul_f32_e32 v73, 0xbfb8aa3b, v65
	v_mul_f32_e32 v74, 0xbfb8aa3b, v66
	v_mul_f32_e32 v75, 0xbfb8aa3b, v67
	v_exp_f32_e32 v72, v72
	v_exp_f32_e32 v73, v73
	v_exp_f32_e32 v74, v74
	v_exp_f32_e32 v75, v75
	v_add_f32_e32 v72, 1.0, v72
	v_add_f32_e32 v73, 1.0, v73
	v_add_f32_e32 v74, 1.0, v74
	v_add_f32_e32 v75, 1.0, v75
	v_rcp_f32_e32 v72, v72
	v_rcp_f32_e32 v73, v73
	v_rcp_f32_e32 v74, v74
	v_rcp_f32_e32 v75, v75
	v_pk_mul_f32 v[72:73], v[64:65], v[72:73]
	s_nop 0
	v_pk_mul_f32 v[72:73], v[72:73], v[68:69]
	v_pk_mul_f32 v[74:75], v[66:67], v[74:75]
	v_cvt_pk_bf16_f32 v72, v72, v73
	v_pk_mul_f32 v[74:75], v[74:75], v[70:71]
	s_nop 0
	v_cvt_pk_bf16_f32 v73, v74, v75
	v_mov_b64_e32 v[74:75], s[52:53]
	v_mad_i64_i32 v[74:75], s[42:43], v121, s39, v[74:75]
	v_lshl_add_u64 v[74:75], v[196:197], 1, v[74:75]
	global_store_dwordx2 v[74:75], v[72:73], off

.LBB0_1491:
	v_pk_fma_f32 v[44:45], v[44:45], v[206:207], v[24:25]
	v_mov_b32_e32 v118, v206
	v_mov_b32_e32 v119, v206
	v_cndmask_b32_e64 v116, 0, v44, s[18:19]
	v_pk_fma_f32 v[46:47], v[46:47], v[118:119], v[26:27]
	v_cndmask_b32_e64 v117, 0, v45, s[18:19]
	v_cndmask_b32_e64 v45, v84, v116, s[2:3]
	v_cndmask_b32_e64 v114, 0, v46, s[18:19]
	v_cndmask_b32_e64 v46, v85, v117, s[2:3]
	v_mov_b32_dpp v44, v45 row_ror:15 row_mask:0xf bank_mask:0xf
	v_cndmask_b32_e64 v115, 0, v47, s[18:19]
	v_cndmask_b32_e64 v47, v86, v114, s[2:3]
	v_mov_b32_dpp v45, v46 row_ror:15 row_mask:0xf bank_mask:0xf
	v_mov_b32_e32 v124, 0
	v_mov_b32_dpp v46, v47 row_ror:15 row_mask:0xf bank_mask:0xf
	v_cndmask_b32_e64 v105, v87, v115, s[2:3]
	v_mov_b32_dpp v113, v84 row_ror:1 row_mask:0xf bank_mask:0xf
	v_mov_b32_dpp v122, v85 row_ror:1 row_mask:0xf bank_mask:0xf
	v_mov_b32_dpp v123, v86 row_ror:1 row_mask:0xf bank_mask:0xf
	v_mov_b32_dpp v124, v87 row_ror:1 row_mask:0xf bank_mask:0xf
	v_mov_b32_dpp v47, v105 row_ror:15 row_mask:0xf bank_mask:0xf
	s_and_b64 vcc, exec, s[20:21]
	v_mov_b32_e32 v105, 0
	v_mov_b32_e32 v106, 0
	v_mov_b32_e32 v107, 0
	s_cbranch_vccnz .LBB0_1493
	v_lshl_add_u32 v104, v226, 2, s8
	ds_read_b128 v[104:107], v104
.LBB0_1493:
	s_waitcnt lgkmcnt(0)
	v_cndmask_b32_e64 v110, v123, v110, s[2:3]
	v_cndmask_b32_e64 v111, v124, v111, s[2:3]
	v_cndmask_b32_e64 v108, v113, v108, s[2:3]
	v_cndmask_b32_e64 v109, v122, v109, s[2:3]
	s_waitcnt vmcnt(7)
	v_pk_mul_f32 v[110:111], v[102:103], v[110:111]
	v_pk_mul_f32 v[108:109], v[100:101], v[108:109]
	s_waitcnt vmcnt(6)
	v_pk_fma_f32 v[110:111], v[86:87], v[98:99], v[110:111]
	v_pk_fma_f32 v[40:41], v[40:41], v[206:207], v[28:29]
	v_pk_fma_f32 v[108:109], v[84:85], v[96:97], v[108:109]
	s_waitcnt vmcnt(5)
	v_pk_fma_f32 v[46:47], v[94:95], v[46:47], v[110:111]
	v_pk_fma_f32 v[42:43], v[42:43], v[118:119], v[30:31]
	v_cndmask_b32_e64 v111, 0, v41, s[18:19]
	v_cndmask_b32_e64 v110, 0, v40, s[18:19]
	v_pk_fma_f32 v[44:45], v[92:93], v[44:45], v[108:109]
	v_cndmask_b32_e64 v108, 0, v42, s[18:19]
	v_mov_b32_dpp v40, v80 row_ror:1 row_mask:0xf bank_mask:0xf
	v_mov_b32_dpp v41, v81 row_ror:1 row_mask:0xf bank_mask:0xf
	v_cndmask_b32_e64 v109, 0, v43, s[18:19]
	v_cndmask_b32_e64 v40, v40, v104, s[2:3]
	v_cndmask_b32_e64 v41, v41, v105, s[2:3]
	v_mov_b32_dpp v42, v82 row_ror:1 row_mask:0xf bank_mask:0xf
	v_cndmask_b32_e64 v105, v80, v110, s[2:3]
	v_cndmask_b32_e64 v42, v42, v106, s[2:3]
	v_mov_b32_dpp v43, v83 row_ror:1 row_mask:0xf bank_mask:0xf
	v_mov_b32_dpp v104, v105 row_ror:15 row_mask:0xf bank_mask:0xf
	v_cndmask_b32_e64 v106, v81, v111, s[2:3]
	v_cndmask_b32_e64 v43, v43, v107, s[2:3]
	v_cndmask_b32_e64 v107, v82, v108, s[2:3]
	v_mov_b32_dpp v105, v106 row_ror:15 row_mask:0xf bank_mask:0xf
	v_cndmask_b32_e64 v113, v83, v109, s[2:3]
	s_waitcnt vmcnt(3)
	v_pk_mul_f32 v[42:43], v[74:75], v[42:43]
	v_mov_b32_dpp v106, v107 row_ror:15 row_mask:0xf bank_mask:0xf
	v_pk_mul_f32 v[40:41], v[72:73], v[40:41]
	s_waitcnt vmcnt(2)
	v_pk_fma_f32 v[42:43], v[82:83], v[66:67], v[42:43]
	v_mov_b32_dpp v107, v113 row_ror:15 row_mask:0xf bank_mask:0xf
	v_pk_fma_f32 v[40:41], v[80:81], v[64:65], v[40:41]
	s_waitcnt vmcnt(1)
	v_pk_fma_f32 v[42:43], v[70:71], v[106:107], v[42:43]
	v_pk_fma_f32 v[40:41], v[68:69], v[104:105], v[40:41]
	v_pk_add_f32 v[46:47], v[90:91], v[46:47]
	v_pk_add_f32 v[44:45], v[88:89], v[44:45]
	s_waitcnt vmcnt(0)
	v_pk_add_f32 v[42:43], v[78:79], v[42:43]
	v_pk_add_f32 v[40:41], v[76:77], v[40:41]
	s_and_saveexec_b64 s[18:19], s[92:93]
	s_cbranch_execz .LBB0_1495
	v_mul_f32_e32 v104, 0xbfb8aa3b, v44
	v_mul_f32_e32 v105, 0xbfb8aa3b, v45
	v_mul_f32_e32 v106, 0xbfb8aa3b, v46
	v_mul_f32_e32 v107, 0xbfb8aa3b, v47
	v_exp_f32_e32 v104, v104
	v_exp_f32_e32 v105, v105
	v_exp_f32_e32 v106, v106
	v_exp_f32_e32 v107, v107
	v_add_f32_e32 v104, 1.0, v104
	v_add_f32_e32 v105, 1.0, v105
	v_add_f32_e32 v106, 1.0, v106
	v_add_f32_e32 v107, 1.0, v107
	v_rcp_f32_e32 v104, v104
	v_rcp_f32_e32 v105, v105
	v_rcp_f32_e32 v106, v106
	v_rcp_f32_e32 v107, v107
	v_pk_mul_f32 v[104:105], v[44:45], v[104:105]
	s_nop 0
	v_pk_mul_f32 v[104:105], v[104:105], v[40:41]
	v_pk_mul_f32 v[106:107], v[46:47], v[106:107]
	v_cvt_pk_bf16_f32 v104, v104, v105
	v_pk_mul_f32 v[106:107], v[106:107], v[42:43]
	s_nop 0
	v_cvt_pk_bf16_f32 v105, v106, v107
	v_mov_b64_e32 v[106:107], s[52:53]
	v_mad_i64_i32 v[106:107], s[8:9], v202, s39, v[106:107]
	v_lshl_add_u64 v[106:107], v[196:197], 1, v[106:107]
	global_store_dwordx2 v[106:107], v[104:105], off offset:32

.LBB0_1497:
	s_or_b64 exec, exec, s[18:19]
	v_mov_b32_e32 v205, v204
	v_mov_b32_e32 v40, v204
	v_mov_b32_e32 v41, v204
	v_pk_fma_f32 v[32:33], v[32:33], v[204:205], v[28:29]
	v_pk_fma_f32 v[38:39], v[38:39], v[40:41], v[26:27]
	v_pk_fma_f32 v[34:35], v[34:35], v[40:41], v[30:31]
	v_cndmask_b32_e64 v40, 0, v32, s[16:17]
	v_cndmask_b32_e64 v32, v116, v84, s[0:1]
	v_mov_b32_e32 v45, 0
	v_pk_fma_f32 v[42:43], v[36:37], v[204:205], v[24:25]
	v_mov_b32_dpp v44, v32 row_ror:1 row_mask:0xf bank_mask:0xf
	v_cndmask_b32_e64 v32, v117, v85, s[0:1]
	v_cndmask_b32_e64 v42, 0, v42, s[16:17]
	v_cndmask_b32_e64 v36, 0, v38, s[16:17]
	v_mov_b32_dpp v45, v32 row_ror:1 row_mask:0xf bank_mask:0xf
	v_cndmask_b32_e64 v32, v114, v86, s[0:1]
	v_cndmask_b32_e64 v43, 0, v43, s[16:17]
	v_cndmask_b32_e64 v38, 0, v34, s[16:17]
	v_mov_b32_dpp v86, v32 row_ror:1 row_mask:0xf bank_mask:0xf
	v_cndmask_b32_e64 v32, v115, v87, s[0:1]
	v_mov_b32_e32 v34, 0
	v_cndmask_b32_e64 v37, 0, v39, s[16:17]
	v_mov_b32_dpp v87, v32 row_ror:1 row_mask:0xf bank_mask:0xf
	v_cndmask_b32_e64 v32, v116, v42, s[2:3]
	v_cndmask_b32_e64 v39, 0, v35, s[16:17]
	v_mov_b32_e32 v35, 0
	v_mov_b32_dpp v34, v32 row_ror:15 row_mask:0xf bank_mask:0xf
	v_cndmask_b32_e64 v32, v117, v43, s[2:3]
	v_mov_b32_e32 v84, 0
	v_mov_b32_e32 v85, 0
	v_mov_b32_dpp v35, v32 row_ror:15 row_mask:0xf bank_mask:0xf
	v_cndmask_b32_e64 v32, v114, v36, s[2:3]
	v_cndmask_b32_e64 v41, 0, v33, s[16:17]
	v_cndmask_b32_e64 v33, v110, v80, s[0:1]
	v_mov_b32_dpp v84, v32 row_ror:15 row_mask:0xf bank_mask:0xf
	v_cndmask_b32_e64 v32, v115, v37, s[2:3]
	v_cndmask_b32_e64 v46, v111, v81, s[0:1]
	v_cndmask_b32_e64 v47, v110, v40, s[2:3]
	v_mov_b32_dpp v85, v32 row_ror:15 row_mask:0xf bank_mask:0xf
	v_cndmask_b32_e64 v80, v111, v41, s[2:3]
	v_cndmask_b32_e64 v81, v108, v38, s[2:3]
	v_mov_b32_dpp v32, v33 row_ror:1 row_mask:0xf bank_mask:0xf
	v_cndmask_b32_e64 v104, v109, v39, s[2:3]
	s_nop 0
	v_mov_b32_dpp v33, v46 row_ror:1 row_mask:0xf bank_mask:0xf
	v_cndmask_b32_e64 v46, v108, v82, s[0:1]
	s_nop 1
	v_mov_b32_dpp v82, v46 row_ror:1 row_mask:0xf bank_mask:0xf
	v_cndmask_b32_e64 v46, v109, v83, s[0:1]
	s_nop 1
	v_mov_b32_dpp v83, v46 row_ror:1 row_mask:0xf bank_mask:0xf
	s_nop 1
	v_mov_b32_dpp v46, v47 row_ror:15 row_mask:0xf bank_mask:0xf
	s_nop 1
	v_mov_b32_dpp v47, v80 row_ror:15 row_mask:0xf bank_mask:0xf
	s_nop 1
	v_mov_b32_dpp v80, v81 row_ror:15 row_mask:0xf bank_mask:0xf
	s_nop 1
	v_mov_b32_dpp v81, v104 row_ror:15 row_mask:0xf bank_mask:0xf
	s_and_saveexec_b64 s[16:17], s[94:95]
	s_cbranch_execz .LBB0_1499
	v_pk_mul_f32 v[44:45], v[100:101], v[44:45]
	v_pk_mul_f32 v[86:87], v[102:103], v[86:87]
	v_pk_fma_f32 v[44:45], v[116:117], v[96:97], v[44:45]
	v_pk_fma_f32 v[86:87], v[114:115], v[98:99], v[86:87]
	v_pk_fma_f32 v[34:35], v[92:93], v[34:35], v[44:45]
	v_pk_mul_f32 v[82:83], v[74:75], v[82:83]
	v_pk_mul_f32 v[32:33], v[72:73], v[32:33]
	v_pk_fma_f32 v[84:85], v[94:95], v[84:85], v[86:87]
	v_pk_add_f32 v[34:35], v[88:89], v[34:35]
	v_pk_fma_f32 v[82:83], v[108:109], v[66:67], v[82:83]
	v_pk_fma_f32 v[32:33], v[110:111], v[64:65], v[32:33]
	v_pk_add_f32 v[44:45], v[90:91], v[84:85]
	v_pk_fma_f32 v[32:33], v[68:69], v[46:47], v[32:33]
	v_pk_fma_f32 v[46:47], v[70:71], v[80:81], v[82:83]
	v_mul_f32_e32 v80, 0xbfb8aa3b, v34
	v_mul_f32_e32 v81, 0xbfb8aa3b, v35
	v_exp_f32_e32 v80, v80
	v_exp_f32_e32 v81, v81
	v_mul_f32_e32 v82, 0xbfb8aa3b, v44
	v_mul_f32_e32 v83, 0xbfb8aa3b, v45
	v_exp_f32_e32 v82, v82
	v_exp_f32_e32 v83, v83
	v_add_f32_e32 v80, 1.0, v80
	v_add_f32_e32 v81, 1.0, v81
	v_rcp_f32_e32 v80, v80
	v_rcp_f32_e32 v81, v81
	v_add_f32_e32 v82, 1.0, v82
	v_add_f32_e32 v83, 1.0, v83
	v_rcp_f32_e32 v82, v82
	v_rcp_f32_e32 v83, v83
	v_pk_add_f32 v[32:33], v[76:77], v[32:33]
	v_pk_mul_f32 v[34:35], v[34:35], v[80:81]
	v_pk_add_f32 v[46:47], v[78:79], v[46:47]
	v_pk_mul_f32 v[32:33], v[34:35], v[32:33]
	v_pk_mul_f32 v[34:35], v[44:45], v[82:83]
	v_cvt_pk_bf16_f32 v32, v32, v33
	v_pk_mul_f32 v[34:35], v[34:35], v[46:47]
	s_nop 0
	v_cvt_pk_bf16_f32 v33, v34, v35
	v_mov_b64_e32 v[34:35], s[52:53]
	v_mad_i64_i32 v[34:35], s[8:9], v199, s39, v[34:35]
	v_lshl_add_u64 v[34:35], v[196:197], 1, v[34:35]
	global_store_dwordx2 v[34:35], v[32:33], off offset:32
.LBB0_1499:
	s_or_b64 exec, exec, s[16:17]
	v_cndmask_b32_e64 v32, v42, v116, s[0:1]
	v_mov_b32_e32 v45, 0
	v_mov_b32_e32 v86, 0
	v_mov_b32_dpp v44, v32 row_ror:1 row_mask:0xf bank_mask:0xf
	v_cndmask_b32_e64 v32, v43, v117, s[0:1]
	v_mov_b32_e32 v87, 0
	v_mov_b32_e32 v34, 0
	v_mov_b32_dpp v45, v32 row_ror:1 row_mask:0xf bank_mask:0xf
	v_cndmask_b32_e64 v32, v36, v114, s[0:1]
	v_mov_b32_e32 v35, 0
	v_mov_b32_e32 v84, 0
	v_mov_b32_dpp v86, v32 row_ror:1 row_mask:0xf bank_mask:0xf
	v_cndmask_b32_e64 v32, v37, v115, s[0:1]
	v_mov_b32_e32 v85, 0
	v_cndmask_b32_e64 v33, v40, v110, s[0:1]
	v_mov_b32_dpp v87, v32 row_ror:1 row_mask:0xf bank_mask:0xf
	v_cndmask_b32_e64 v32, v42, v56, s[2:3]
	v_cndmask_b32_e64 v46, v41, v111, s[0:1]
	v_mov_b32_e32 v82, 0
	v_mov_b32_dpp v34, v32 row_ror:15 row_mask:0xf bank_mask:0xf
	v_cndmask_b32_e64 v32, v43, v57, s[2:3]
	v_mov_b32_e32 v83, 0
	v_cndmask_b32_e64 v47, v40, v60, s[2:3]
	v_mov_b32_dpp v35, v32 row_ror:15 row_mask:0xf bank_mask:0xf
	v_cndmask_b32_e64 v32, v36, v58, s[2:3]
	v_cndmask_b32_e64 v80, v41, v61, s[2:3]
	v_cndmask_b32_e64 v81, v38, v62, s[2:3]
	v_mov_b32_dpp v84, v32 row_ror:15 row_mask:0xf bank_mask:0xf
	v_cndmask_b32_e64 v32, v37, v59, s[2:3]
	v_cndmask_b32_e64 v104, v39, v63, s[2:3]
	s_nop 0
	v_mov_b32_dpp v85, v32 row_ror:15 row_mask:0xf bank_mask:0xf
	s_nop 1
	v_mov_b32_dpp v32, v33 row_ror:1 row_mask:0xf bank_mask:0xf
	s_nop 1
	v_mov_b32_dpp v33, v46 row_ror:1 row_mask:0xf bank_mask:0xf
	v_cndmask_b32_e64 v46, v38, v108, s[0:1]
	s_nop 1
	v_mov_b32_dpp v82, v46 row_ror:1 row_mask:0xf bank_mask:0xf
	v_cndmask_b32_e64 v46, v39, v109, s[0:1]
	s_nop 1
	v_mov_b32_dpp v83, v46 row_ror:1 row_mask:0xf bank_mask:0xf
	s_nop 1
	v_mov_b32_dpp v46, v47 row_ror:15 row_mask:0xf bank_mask:0xf
	s_nop 1
	v_mov_b32_dpp v47, v80 row_ror:15 row_mask:0xf bank_mask:0xf
	s_nop 1
	v_mov_b32_dpp v80, v81 row_ror:15 row_mask:0xf bank_mask:0xf
	s_nop 1
	v_mov_b32_dpp v81, v104 row_ror:15 row_mask:0xf bank_mask:0xf
	s_and_saveexec_b64 s[16:17], s[96:97]
	s_cbranch_execz .LBB0_1501
	v_pk_mul_f32 v[44:45], v[100:101], v[44:45]
	v_pk_mul_f32 v[86:87], v[102:103], v[86:87]
	v_pk_fma_f32 v[44:45], v[42:43], v[96:97], v[44:45]
	v_pk_fma_f32 v[86:87], v[36:37], v[98:99], v[86:87]
	v_pk_fma_f32 v[34:35], v[92:93], v[34:35], v[44:45]
	v_pk_mul_f32 v[82:83], v[74:75], v[82:83]
	v_pk_mul_f32 v[32:33], v[72:73], v[32:33]
	v_pk_fma_f32 v[84:85], v[94:95], v[84:85], v[86:87]
	v_pk_add_f32 v[34:35], v[88:89], v[34:35]
	v_pk_fma_f32 v[82:83], v[38:39], v[66:67], v[82:83]
	v_pk_fma_f32 v[32:33], v[40:41], v[64:65], v[32:33]
	v_pk_add_f32 v[44:45], v[90:91], v[84:85]
	v_pk_fma_f32 v[32:33], v[68:69], v[46:47], v[32:33]
	v_pk_fma_f32 v[46:47], v[70:71], v[80:81], v[82:83]
	v_mul_f32_e32 v80, 0xbfb8aa3b, v34
	v_mul_f32_e32 v81, 0xbfb8aa3b, v35
	v_exp_f32_e32 v80, v80
	v_exp_f32_e32 v81, v81
	v_mul_f32_e32 v82, 0xbfb8aa3b, v44
	v_mul_f32_e32 v83, 0xbfb8aa3b, v45
	v_exp_f32_e32 v82, v82
	v_exp_f32_e32 v83, v83
	v_add_f32_e32 v80, 1.0, v80
	v_add_f32_e32 v81, 1.0, v81
	v_rcp_f32_e32 v80, v80
	v_rcp_f32_e32 v81, v81
	v_add_f32_e32 v82, 1.0, v82
	v_add_f32_e32 v83, 1.0, v83
	v_rcp_f32_e32 v82, v82
	v_rcp_f32_e32 v83, v83
	v_pk_add_f32 v[32:33], v[76:77], v[32:33]
	v_pk_mul_f32 v[34:35], v[34:35], v[80:81]
	v_pk_add_f32 v[46:47], v[78:79], v[46:47]
	v_pk_mul_f32 v[32:33], v[34:35], v[32:33]
	v_pk_mul_f32 v[34:35], v[44:45], v[82:83]
	v_cvt_pk_bf16_f32 v32, v32, v33
	v_pk_mul_f32 v[34:35], v[34:35], v[46:47]
	s_nop 0
	v_cvt_pk_bf16_f32 v33, v34, v35
	v_mov_b64_e32 v[34:35], s[52:53]
	v_mad_i64_i32 v[34:35], s[8:9], v176, s39, v[34:35]
	v_lshl_add_u64 v[34:35], v[196:197], 1, v[34:35]
	global_store_dwordx2 v[34:35], v[32:33], off offset:32
.LBB0_1501:
	s_or_b64 exec, exec, s[16:17]
	v_cndmask_b32_e64 v32, v56, v42, s[0:1]
	v_mov_b32_e32 v46, 0
	v_mov_b32_e32 v47, 0
	v_mov_b32_dpp v42, v32 row_ror:1 row_mask:0xf bank_mask:0xf
	v_cndmask_b32_e64 v32, v57, v43, s[0:1]
	s_and_b64 vcc, exec, s[22:23]
	v_mov_b32_e32 v33, 0
	v_mov_b32_dpp v43, v32 row_ror:1 row_mask:0xf bank_mask:0xf
	v_cndmask_b32_e64 v32, v58, v36, s[0:1]
	v_mov_b32_e32 v36, 0
	v_mov_b32_e32 v34, 0
	v_mov_b32_dpp v46, v32 row_ror:1 row_mask:0xf bank_mask:0xf
	v_cndmask_b32_e64 v32, v59, v37, s[0:1]
	v_mov_b32_e32 v35, 0
	s_nop 0
	v_mov_b32_dpp v47, v32 row_ror:1 row_mask:0xf bank_mask:0xf
	v_mov_b32_e32 v32, 0
	s_cbranch_vccnz .LBB0_1503
	ds_read_b128 v[32:35], v168 offset:2112
.LBB0_1503:
	v_cndmask_b32_e64 v37, v60, v40, s[0:1]
	v_mov_b32_e32 v44, 0
	v_mov_b32_e32 v80, 0
	v_mov_b32_dpp v40, v37 row_ror:1 row_mask:0xf bank_mask:0xf
	v_cndmask_b32_e64 v37, v61, v41, s[0:1]
	v_mov_b32_e32 v81, 0
	v_mov_b32_e32 v82, 0
	v_mov_b32_dpp v41, v37 row_ror:1 row_mask:0xf bank_mask:0xf
	v_cndmask_b32_e64 v37, v62, v38, s[0:1]
	v_mov_b32_e32 v83, 0
	v_mov_b32_e32 v45, 0
	v_mov_b32_dpp v44, v37 row_ror:1 row_mask:0xf bank_mask:0xf
	v_cndmask_b32_e64 v37, v63, v39, s[0:1]
	v_mov_b32_dpp v80, v56 row_ror:15 row_mask:0xf bank_mask:0xf
	v_mov_b32_dpp v81, v57 row_ror:15 row_mask:0xf bank_mask:0xf
	v_mov_b32_dpp v82, v58 row_ror:15 row_mask:0xf bank_mask:0xf
	v_mov_b32_dpp v83, v59 row_ror:15 row_mask:0xf bank_mask:0xf
	v_mov_b32_dpp v45, v37 row_ror:1 row_mask:0xf bank_mask:0xf
	s_and_b64 vcc, exec, s[22:23]
	v_mov_b32_e32 v37, 0
	v_mov_b32_e32 v38, 0
	v_mov_b32_e32 v39, 0
	s_cbranch_vccnz .LBB0_1505
	ds_read_b128 v[36:39], v168 offset:2624
.LBB0_1505:
	v_pk_mul_f32 v[42:43], v[100:101], v[42:43]
	s_waitcnt lgkmcnt(0)
	v_cndmask_b32_e64 v32, v80, v32, s[0:1]
	v_cndmask_b32_e64 v33, v81, v33, s[0:1]
	v_pk_mul_f32 v[46:47], v[102:103], v[46:47]
	v_pk_fma_f32 v[42:43], v[56:57], v[96:97], v[42:43]
	v_cndmask_b32_e64 v34, v82, v34, s[0:1]
	v_cndmask_b32_e64 v35, v83, v35, s[0:1]
	v_pk_fma_f32 v[46:47], v[58:59], v[98:99], v[46:47]
	v_pk_fma_f32 v[32:33], v[92:93], v[32:33], v[42:43]
	v_pk_fma_f32 v[34:35], v[94:95], v[34:35], v[46:47]
	v_mov_b32_dpp v42, v60 row_ror:15 row_mask:0xf bank_mask:0xf
	v_mov_b32_dpp v43, v61 row_ror:15 row_mask:0xf bank_mask:0xf
	v_cndmask_b32_e64 v36, v42, v36, s[0:1]
	v_mov_b32_dpp v46, v62 row_ror:15 row_mask:0xf bank_mask:0xf
	v_mov_b32_dpp v47, v63 row_ror:15 row_mask:0xf bank_mask:0xf
	v_cndmask_b32_e64 v37, v43, v37, s[0:1]
	v_pk_mul_f32 v[42:43], v[74:75], v[44:45]
	v_pk_mul_f32 v[40:41], v[72:73], v[40:41]
	v_cndmask_b32_e64 v38, v46, v38, s[0:1]
	v_cndmask_b32_e64 v39, v47, v39, s[0:1]
	v_pk_fma_f32 v[42:43], v[62:63], v[66:67], v[42:43]
	v_pk_fma_f32 v[40:41], v[60:61], v[64:65], v[40:41]
	v_pk_fma_f32 v[38:39], v[70:71], v[38:39], v[42:43]
	v_pk_fma_f32 v[36:37], v[68:69], v[36:37], v[40:41]
	v_pk_add_f32 v[32:33], v[88:89], v[32:33]
	v_pk_add_f32 v[34:35], v[90:91], v[34:35]
	v_pk_add_f32 v[38:39], v[78:79], v[38:39]
	v_pk_add_f32 v[36:37], v[76:77], v[36:37]
	s_and_saveexec_b64 s[16:17], s[84:85]
	s_cbranch_execz .LBB0_1507
	v_mul_f32_e32 v40, 0xbfb8aa3b, v32
	v_mul_f32_e32 v41, 0xbfb8aa3b, v33
	v_mul_f32_e32 v42, 0xbfb8aa3b, v34
	v_mul_f32_e32 v43, 0xbfb8aa3b, v35
	v_exp_f32_e32 v40, v40
	v_exp_f32_e32 v41, v41
	v_exp_f32_e32 v42, v42
	v_exp_f32_e32 v43, v43
	v_add_f32_e32 v40, 1.0, v40
	v_add_f32_e32 v41, 1.0, v41
	v_add_f32_e32 v42, 1.0, v42
	v_add_f32_e32 v43, 1.0, v43
	v_rcp_f32_e32 v40, v40
	v_rcp_f32_e32 v41, v41
	v_rcp_f32_e32 v42, v42
	v_rcp_f32_e32 v43, v43
	v_pk_mul_f32 v[40:41], v[32:33], v[40:41]
	s_nop 0
	v_pk_mul_f32 v[40:41], v[40:41], v[36:37]
	v_pk_mul_f32 v[42:43], v[34:35], v[42:43]
	v_cvt_pk_bf16_f32 v40, v40, v41
	v_pk_mul_f32 v[42:43], v[42:43], v[38:39]
	s_nop 0
	v_cvt_pk_bf16_f32 v41, v42, v43
	v_mov_b64_e32 v[42:43], s[52:53]
	v_mad_i64_i32 v[42:43], s[8:9], v169, s39, v[42:43]
	v_lshl_add_u64 v[42:43], v[196:197], 1, v[42:43]
	global_store_dwordx2 v[42:43], v[40:41], off offset:32

.LBB0_1509:
	s_or_b64 exec, exec, s[16:17]
	v_mov_b32_e32 v201, v200
	v_mov_b32_e32 v32, v200
	v_mov_b32_e32 v33, v200
	v_pk_fma_f32 v[14:15], v[14:15], v[32:33], v[26:27]
	v_pk_fma_f32 v[34:35], v[12:13], v[200:201], v[24:25]
	v_cndmask_b32_e64 v12, 0, v14, s[14:15]
	v_cndmask_b32_e64 v14, 0, v34, s[14:15]
	v_pk_fma_f32 v[10:11], v[10:11], v[32:33], v[30:31]
	v_pk_fma_f32 v[32:33], v[8:9], v[200:201], v[28:29]
	v_cndmask_b32_e64 v13, 0, v15, s[14:15]
	v_cndmask_b32_e64 v15, 0, v35, s[14:15]
	v_cndmask_b32_e64 v9, 0, v11, s[14:15]
	v_cndmask_b32_e64 v8, 0, v10, s[14:15]
	v_cndmask_b32_e64 v11, 0, v33, s[14:15]
	v_cndmask_b32_e64 v10, 0, v32, s[14:15]
	v_cndmask_b32_e64 v33, v52, v14, s[2:3]
	v_cndmask_b32_e64 v34, v53, v15, s[2:3]
	v_cndmask_b32_e64 v35, v54, v12, s[2:3]
	v_mov_b32_dpp v32, v33 row_ror:15 row_mask:0xf bank_mask:0xf
	v_cndmask_b32_e64 v36, v55, v13, s[2:3]
	v_cndmask_b32_e64 v37, v48, v10, s[2:3]
	v_mov_b32_dpp v33, v34 row_ror:15 row_mask:0xf bank_mask:0xf
	v_cndmask_b32_e64 v38, v49, v11, s[2:3]
	v_cndmask_b32_e64 v39, v50, v8, s[2:3]
	v_mov_b32_dpp v34, v35 row_ror:15 row_mask:0xf bank_mask:0xf
	v_mov_b32_dpp v35, v36 row_ror:15 row_mask:0xf bank_mask:0xf
	v_mov_b32_dpp v36, v37 row_ror:15 row_mask:0xf bank_mask:0xf
	v_mov_b32_dpp v37, v38 row_ror:15 row_mask:0xf bank_mask:0xf
	v_mov_b32_dpp v38, v39 row_ror:15 row_mask:0xf bank_mask:0xf
	v_cndmask_b32_e64 v56, v51, v9, s[2:3]
	v_mov_b32_dpp v40, v52 row_ror:1 row_mask:0xf bank_mask:0xf
	v_mov_b32_dpp v41, v53 row_ror:1 row_mask:0xf bank_mask:0xf
	v_mov_b32_dpp v42, v54 row_ror:1 row_mask:0xf bank_mask:0xf
	v_mov_b32_dpp v43, v55 row_ror:1 row_mask:0xf bank_mask:0xf
	v_mov_b32_dpp v44, v48 row_ror:1 row_mask:0xf bank_mask:0xf
	v_mov_b32_dpp v45, v49 row_ror:1 row_mask:0xf bank_mask:0xf
	v_mov_b32_dpp v46, v50 row_ror:1 row_mask:0xf bank_mask:0xf
	v_mov_b32_dpp v47, v51 row_ror:1 row_mask:0xf bank_mask:0xf
	v_mov_b32_dpp v39, v56 row_ror:15 row_mask:0xf bank_mask:0xf
	s_and_saveexec_b64 s[14:15], s[34:35]
	s_cbranch_execz .LBB0_1511
	ds_read_b128 v[56:59], v168 offset:3648
	s_waitcnt lgkmcnt(0)
	v_cndmask_b32_e64 v44, v44, v56, s[2:3]
	v_cndmask_b32_e64 v45, v45, v57, s[2:3]
	v_cndmask_b32_e64 v46, v46, v58, s[2:3]
	v_cndmask_b32_e64 v47, v47, v59, s[2:3]
	v_pk_mul_f32 v[44:45], v[72:73], v[44:45]
	v_pk_mul_f32 v[46:47], v[74:75], v[46:47]
	v_pk_fma_f32 v[44:45], v[48:49], v[64:65], v[44:45]
	v_pk_fma_f32 v[46:47], v[50:51], v[66:67], v[46:47]
	v_pk_fma_f32 v[36:37], v[68:69], v[36:37], v[44:45]
	v_pk_fma_f32 v[38:39], v[70:71], v[38:39], v[46:47]
	v_pk_add_f32 v[46:47], v[76:77], v[36:37]
	v_pk_add_f32 v[44:45], v[78:79], v[38:39]
	ds_read_b128 v[36:39], v168 offset:3136
	s_waitcnt lgkmcnt(0)
	v_cndmask_b32_e64 v36, v40, v36, s[2:3]
	v_cndmask_b32_e64 v37, v41, v37, s[2:3]
	v_pk_mul_f32 v[36:37], v[100:101], v[36:37]
	v_cndmask_b32_e64 v38, v42, v38, s[2:3]
	v_pk_fma_f32 v[36:37], v[52:53], v[96:97], v[36:37]
	v_cndmask_b32_e64 v39, v43, v39, s[2:3]
	v_pk_fma_f32 v[32:33], v[92:93], v[32:33], v[36:37]
	v_pk_mul_f32 v[38:39], v[102:103], v[38:39]
	v_pk_add_f32 v[32:33], v[88:89], v[32:33]
	v_pk_fma_f32 v[38:39], v[54:55], v[98:99], v[38:39]
	v_mul_f32_e32 v36, 0xbfb8aa3b, v32
	v_mul_f32_e32 v37, 0xbfb8aa3b, v33
	v_exp_f32_e32 v36, v36
	v_exp_f32_e32 v37, v37
	v_pk_fma_f32 v[34:35], v[94:95], v[34:35], v[38:39]
	v_add_f32_e32 v36, 1.0, v36
	v_add_f32_e32 v37, 1.0, v37
	v_rcp_f32_e32 v36, v36
	v_rcp_f32_e32 v37, v37
	v_pk_add_f32 v[34:35], v[90:91], v[34:35]
	v_pk_mul_f32 v[32:33], v[32:33], v[36:37]
	v_mul_f32_e32 v36, 0xbfb8aa3b, v34
	v_mul_f32_e32 v37, 0xbfb8aa3b, v35
	v_exp_f32_e32 v36, v36
	v_exp_f32_e32 v37, v37
	v_pk_mul_f32 v[32:33], v[46:47], v[32:33]
	v_add_f32_e32 v36, 1.0, v36
	v_add_f32_e32 v37, 1.0, v37
	v_rcp_f32_e32 v36, v36
	v_rcp_f32_e32 v37, v37
	v_cvt_pk_bf16_f32 v32, v32, v33
	v_pk_mul_f32 v[34:35], v[34:35], v[36:37]
	s_nop 0
	v_pk_mul_f32 v[34:35], v[44:45], v[34:35]
	s_nop 0
	v_cvt_pk_bf16_f32 v33, v34, v35
	v_mov_b64_e32 v[34:35], s[52:53]
	v_mad_i64_i32 v[34:35], s[8:9], v160, s39, v[34:35]
	v_lshl_add_u64 v[34:35], v[196:197], 1, v[34:35]
	global_store_dwordx2 v[34:35], v[32:33], off offset:32
.LBB0_1511:
	s_or_b64 exec, exec, s[14:15]
	v_mov_b32_e32 v199, v198
	v_mov_b32_e32 v32, v198
	v_mov_b32_e32 v33, v198
	v_pk_fma_f32 v[24:25], v[4:5], v[198:199], v[24:25]
	v_pk_fma_f32 v[0:1], v[0:1], v[198:199], v[28:29]
	v_pk_fma_f32 v[6:7], v[6:7], v[32:33], v[26:27]
	v_cndmask_b32_e64 v26, 0, v24, s[12:13]
	v_cndmask_b32_e64 v24, 0, v0, s[12:13]
	v_cndmask_b32_e64 v0, v14, v52, s[0:1]
	v_mov_b32_e32 v29, 0
	v_mov_b32_e32 v38, 0
	v_mov_b32_dpp v28, v0 row_ror:1 row_mask:0xf bank_mask:0xf
	v_cndmask_b32_e64 v0, v15, v53, s[0:1]
	v_pk_fma_f32 v[2:3], v[2:3], v[32:33], v[30:31]
	v_mov_b32_e32 v39, 0
	v_mov_b32_dpp v29, v0 row_ror:1 row_mask:0xf bank_mask:0xf
	v_cndmask_b32_e64 v0, v12, v54, s[0:1]
	v_cndmask_b32_e64 v4, 0, v6, s[12:13]
	v_cndmask_b32_e64 v27, 0, v25, s[12:13]
	v_mov_b32_dpp v38, v0 row_ror:1 row_mask:0xf bank_mask:0xf
	v_cndmask_b32_e64 v0, v13, v55, s[0:1]
	v_cndmask_b32_e64 v6, 0, v2, s[12:13]
	v_mov_b32_e32 v2, 0
	v_mov_b32_dpp v39, v0 row_ror:1 row_mask:0xf bank_mask:0xf
	v_cndmask_b32_e64 v0, v14, v26, s[2:3]
	v_cndmask_b32_e64 v5, 0, v7, s[12:13]
	v_cndmask_b32_e64 v7, 0, v3, s[12:13]
	v_mov_b32_dpp v2, v0 row_ror:15 row_mask:0xf bank_mask:0xf
	v_cndmask_b32_e64 v0, v15, v27, s[2:3]
	v_mov_b32_e32 v36, 0
	v_mov_b32_e32 v37, 0
	v_mov_b32_dpp v3, v0 row_ror:15 row_mask:0xf bank_mask:0xf
	v_cndmask_b32_e64 v0, v12, v4, s[2:3]
	v_cndmask_b32_e64 v25, 0, v1, s[12:13]
	v_cndmask_b32_e64 v1, v10, v48, s[0:1]
	v_mov_b32_dpp v36, v0 row_ror:15 row_mask:0xf bank_mask:0xf
	v_cndmask_b32_e64 v0, v13, v5, s[2:3]
	v_cndmask_b32_e64 v30, v11, v49, s[0:1]
	v_mov_b32_e32 v34, 0
	v_mov_b32_dpp v37, v0 row_ror:15 row_mask:0xf bank_mask:0xf
	v_cndmask_b32_e64 v31, v10, v24, s[2:3]
	v_mov_b32_dpp v0, v1 row_ror:1 row_mask:0xf bank_mask:0xf
	v_cndmask_b32_e64 v32, v11, v25, s[2:3]
	v_cndmask_b32_e64 v33, v8, v6, s[2:3]
	v_mov_b32_dpp v1, v30 row_ror:1 row_mask:0xf bank_mask:0xf
	v_cndmask_b32_e64 v30, v8, v50, s[0:1]
	v_cndmask_b32_e64 v40, v9, v7, s[2:3]
	s_nop 0
	v_mov_b32_dpp v34, v30 row_ror:1 row_mask:0xf bank_mask:0xf
	v_cndmask_b32_e64 v30, v9, v51, s[0:1]
	s_nop 1
	v_mov_b32_dpp v35, v30 row_ror:1 row_mask:0xf bank_mask:0xf
	s_nop 1
	v_mov_b32_dpp v30, v31 row_ror:15 row_mask:0xf bank_mask:0xf
	s_nop 1
	v_mov_b32_dpp v31, v32 row_ror:15 row_mask:0xf bank_mask:0xf
	s_nop 1
	v_mov_b32_dpp v32, v33 row_ror:15 row_mask:0xf bank_mask:0xf
	s_nop 1
	v_mov_b32_dpp v33, v40 row_ror:15 row_mask:0xf bank_mask:0xf
	s_and_saveexec_b64 s[12:13], s[36:37]
	s_cbranch_execz .LBB0_1513
	v_pk_mul_f32 v[28:29], v[100:101], v[28:29]
	v_pk_mul_f32 v[38:39], v[102:103], v[38:39]
	v_pk_fma_f32 v[28:29], v[14:15], v[96:97], v[28:29]
	v_pk_fma_f32 v[38:39], v[12:13], v[98:99], v[38:39]
	v_pk_fma_f32 v[2:3], v[92:93], v[2:3], v[28:29]
	v_pk_mul_f32 v[34:35], v[74:75], v[34:35]
	v_pk_mul_f32 v[0:1], v[72:73], v[0:1]
	v_pk_fma_f32 v[36:37], v[94:95], v[36:37], v[38:39]
	v_pk_add_f32 v[2:3], v[88:89], v[2:3]
	v_pk_fma_f32 v[34:35], v[8:9], v[66:67], v[34:35]
	v_pk_fma_f32 v[0:1], v[10:11], v[64:65], v[0:1]
	v_pk_add_f32 v[28:29], v[90:91], v[36:37]
	v_pk_fma_f32 v[0:1], v[68:69], v[30:31], v[0:1]
	v_pk_fma_f32 v[30:31], v[70:71], v[32:33], v[34:35]
	v_mul_f32_e32 v32, 0xbfb8aa3b, v2
	v_mul_f32_e32 v33, 0xbfb8aa3b, v3
	v_exp_f32_e32 v32, v32
	v_exp_f32_e32 v33, v33
	v_mul_f32_e32 v34, 0xbfb8aa3b, v28
	v_mul_f32_e32 v35, 0xbfb8aa3b, v29
	v_exp_f32_e32 v34, v34
	v_exp_f32_e32 v35, v35
	v_add_f32_e32 v32, 1.0, v32
	v_add_f32_e32 v33, 1.0, v33
	v_rcp_f32_e32 v32, v32
	v_rcp_f32_e32 v33, v33
	v_add_f32_e32 v34, 1.0, v34
	v_add_f32_e32 v35, 1.0, v35
	v_rcp_f32_e32 v34, v34
	v_rcp_f32_e32 v35, v35
	v_pk_add_f32 v[0:1], v[76:77], v[0:1]
	v_pk_mul_f32 v[2:3], v[2:3], v[32:33]
	v_pk_add_f32 v[30:31], v[78:79], v[30:31]
	v_pk_mul_f32 v[0:1], v[2:3], v[0:1]
	v_pk_mul_f32 v[2:3], v[28:29], v[34:35]
	v_cvt_pk_bf16_f32 v0, v0, v1
	v_pk_mul_f32 v[2:3], v[2:3], v[30:31]
	s_nop 0
	v_cvt_pk_bf16_f32 v1, v2, v3
	v_mov_b64_e32 v[2:3], s[52:53]
	v_mad_i64_i32 v[2:3], s[8:9], v161, s39, v[2:3]
	v_lshl_add_u64 v[2:3], v[196:197], 1, v[2:3]
	global_store_dwordx2 v[2:3], v[0:1], off offset:32
.LBB0_1513:
	s_or_b64 exec, exec, s[12:13]
	v_cndmask_b32_e64 v0, v26, v14, s[0:1]
	v_mov_b32_e32 v30, 0
	v_mov_b32_e32 v31, 0
	v_mov_b32_dpp v14, v0 row_ror:1 row_mask:0xf bank_mask:0xf
	v_cndmask_b32_e64 v0, v27, v15, s[0:1]
	v_mov_b32_e32 v2, 0
	v_mov_b32_e32 v3, 0
	v_mov_b32_dpp v15, v0 row_ror:1 row_mask:0xf bank_mask:0xf
	v_cndmask_b32_e64 v0, v4, v12, s[0:1]
	v_mov_b32_e32 v28, 0
	v_mov_b32_e32 v29, 0
	v_mov_b32_dpp v30, v0 row_ror:1 row_mask:0xf bank_mask:0xf
	v_cndmask_b32_e64 v0, v5, v13, s[0:1]
	v_cndmask_b32_e64 v8, v6, v8, s[0:1]
	v_mov_b32_e32 v12, 0
	v_mov_b32_dpp v31, v0 row_ror:1 row_mask:0xf bank_mask:0xf
	v_cndmask_b32_e64 v0, v26, v16, s[2:3]
	v_cndmask_b32_e64 v1, v24, v10, s[0:1]
	v_mov_b32_dpp v12, v8 row_ror:1 row_mask:0xf bank_mask:0xf
	v_mov_b32_dpp v2, v0 row_ror:15 row_mask:0xf bank_mask:0xf
	v_cndmask_b32_e64 v0, v27, v17, s[2:3]
	v_cndmask_b32_e64 v8, v7, v9, s[0:1]
	v_mov_b32_e32 v13, 0
	v_mov_b32_dpp v3, v0 row_ror:15 row_mask:0xf bank_mask:0xf
	v_cndmask_b32_e64 v0, v4, v18, s[2:3]
	v_cndmask_b32_e64 v10, v25, v11, s[0:1]
	v_mov_b32_dpp v13, v8 row_ror:1 row_mask:0xf bank_mask:0xf
	v_mov_b32_dpp v28, v0 row_ror:15 row_mask:0xf bank_mask:0xf
	v_cndmask_b32_e64 v0, v5, v19, s[2:3]
	v_cndmask_b32_e64 v9, v24, v20, s[2:3]
	v_mov_b32_e32 v8, 0
	v_mov_b32_dpp v29, v0 row_ror:15 row_mask:0xf bank_mask:0xf
	v_mov_b32_e32 v0, 0
	v_mov_b32_dpp v8, v9 row_ror:15 row_mask:0xf bank_mask:0xf
	v_mov_b32_dpp v0, v1 row_ror:1 row_mask:0xf bank_mask:0xf
	v_cndmask_b32_e64 v11, v6, v22, s[2:3]
	v_cndmask_b32_e64 v32, v7, v23, s[2:3]
	v_mov_b32_dpp v1, v10 row_ror:1 row_mask:0xf bank_mask:0xf
	v_cndmask_b32_e64 v10, v25, v21, s[2:3]
	s_nop 1
	v_mov_b32_dpp v9, v10 row_ror:15 row_mask:0xf bank_mask:0xf
	s_nop 1
	v_mov_b32_dpp v10, v11 row_ror:15 row_mask:0xf bank_mask:0xf
	s_nop 1
	v_mov_b32_dpp v11, v32 row_ror:15 row_mask:0xf bank_mask:0xf
	s_and_saveexec_b64 s[12:13], s[40:41]
	s_cbranch_execz .LBB0_1515
	v_pk_mul_f32 v[14:15], v[100:101], v[14:15]
	v_pk_mul_f32 v[30:31], v[102:103], v[30:31]
	v_pk_fma_f32 v[14:15], v[26:27], v[96:97], v[14:15]
	v_pk_fma_f32 v[30:31], v[4:5], v[98:99], v[30:31]
	v_pk_fma_f32 v[2:3], v[92:93], v[2:3], v[14:15]
	v_pk_mul_f32 v[12:13], v[74:75], v[12:13]
	v_pk_mul_f32 v[0:1], v[72:73], v[0:1]
	v_pk_fma_f32 v[28:29], v[94:95], v[28:29], v[30:31]
	v_pk_add_f32 v[2:3], v[88:89], v[2:3]
	v_pk_fma_f32 v[12:13], v[6:7], v[66:67], v[12:13]
	v_pk_fma_f32 v[0:1], v[24:25], v[64:65], v[0:1]
	v_pk_add_f32 v[14:15], v[90:91], v[28:29]
	v_pk_fma_f32 v[0:1], v[68:69], v[8:9], v[0:1]
	v_pk_fma_f32 v[8:9], v[70:71], v[10:11], v[12:13]
	v_mul_f32_e32 v10, 0xbfb8aa3b, v2
	v_mul_f32_e32 v11, 0xbfb8aa3b, v3
	v_exp_f32_e32 v10, v10
	v_exp_f32_e32 v11, v11
	v_mul_f32_e32 v12, 0xbfb8aa3b, v14
	v_mul_f32_e32 v13, 0xbfb8aa3b, v15
	v_exp_f32_e32 v12, v12
	v_exp_f32_e32 v13, v13
	v_add_f32_e32 v10, 1.0, v10
	v_add_f32_e32 v11, 1.0, v11
	v_rcp_f32_e32 v10, v10
	v_rcp_f32_e32 v11, v11
	v_add_f32_e32 v12, 1.0, v12
	v_add_f32_e32 v13, 1.0, v13
	v_rcp_f32_e32 v12, v12
	v_rcp_f32_e32 v13, v13
	v_pk_add_f32 v[0:1], v[76:77], v[0:1]
	v_pk_mul_f32 v[2:3], v[2:3], v[10:11]
	v_pk_add_f32 v[8:9], v[78:79], v[8:9]
	v_pk_mul_f32 v[0:1], v[2:3], v[0:1]
	v_pk_mul_f32 v[2:3], v[14:15], v[12:13]
	v_cvt_pk_bf16_f32 v0, v0, v1
	v_pk_mul_f32 v[2:3], v[2:3], v[8:9]
	s_nop 0
	v_cvt_pk_bf16_f32 v1, v2, v3
	v_mov_b64_e32 v[2:3], s[52:53]
	v_mad_i64_i32 v[2:3], s[8:9], v120, s39, v[2:3]
	v_lshl_add_u64 v[2:3], v[196:197], 1, v[2:3]
	global_store_dwordx2 v[2:3], v[0:1], off offset:32
.LBB0_1515:
	s_or_b64 exec, exec, s[12:13]
	v_cndmask_b32_e64 v0, v16, v26, s[0:1]
	v_mov_b32_e32 v11, 0
	v_mov_b32_e32 v14, 0
	v_mov_b32_dpp v10, v0 row_ror:1 row_mask:0xf bank_mask:0xf
	v_cndmask_b32_e64 v0, v17, v27, s[0:1]
	v_mov_b32_e32 v15, 0
	s_and_b64 vcc, exec, s[24:25]
	v_mov_b32_dpp v11, v0 row_ror:1 row_mask:0xf bank_mask:0xf
	v_cndmask_b32_e64 v0, v18, v4, s[0:1]
	v_mov_b32_e32 v4, 0
	v_mov_b32_e32 v1, 0
	v_mov_b32_dpp v14, v0 row_ror:1 row_mask:0xf bank_mask:0xf
	v_cndmask_b32_e64 v0, v19, v5, s[0:1]
	v_mov_b32_e32 v2, 0
	v_mov_b32_e32 v3, 0
	v_mov_b32_dpp v15, v0 row_ror:1 row_mask:0xf bank_mask:0xf
	v_mov_b32_e32 v0, 0
	s_cbranch_vccnz .LBB0_1517
	ds_read_b128 v[0:3], v168 offset:6208
.LBB0_1517:
	v_cndmask_b32_e64 v5, v20, v24, s[0:1]
	v_mov_b32_e32 v9, 0
	v_mov_b32_e32 v12, 0
	v_mov_b32_dpp v8, v5 row_ror:1 row_mask:0xf bank_mask:0xf
	v_cndmask_b32_e64 v5, v21, v25, s[0:1]
	v_mov_b32_e32 v26, 0
	v_mov_b32_e32 v27, 0
	v_mov_b32_dpp v9, v5 row_ror:1 row_mask:0xf bank_mask:0xf
	v_cndmask_b32_e64 v5, v22, v6, s[0:1]
	v_mov_b32_e32 v28, 0
	v_mov_b32_e32 v29, 0
	v_mov_b32_dpp v12, v5 row_ror:1 row_mask:0xf bank_mask:0xf
	v_cndmask_b32_e64 v5, v23, v7, s[0:1]
	v_mov_b32_dpp v26, v16 row_ror:15 row_mask:0xf bank_mask:0xf
	v_mov_b32_dpp v27, v17 row_ror:15 row_mask:0xf bank_mask:0xf
	v_mov_b32_dpp v28, v18 row_ror:15 row_mask:0xf bank_mask:0xf
	v_mov_b32_dpp v29, v19 row_ror:15 row_mask:0xf bank_mask:0xf
	v_mov_b32_dpp v13, v5 row_ror:1 row_mask:0xf bank_mask:0xf
	s_and_b64 vcc, exec, s[24:25]
	v_mov_b32_e32 v5, 0
	v_mov_b32_e32 v6, 0
	v_mov_b32_e32 v7, 0
	s_cbranch_vccnz .LBB0_1519
	ds_read_b128 v[4:7], v168 offset:6720
.LBB0_1519:
	v_pk_mul_f32 v[10:11], v[100:101], v[10:11]
	s_waitcnt lgkmcnt(0)
	v_cndmask_b32_e64 v0, v26, v0, s[0:1]
	v_cndmask_b32_e64 v1, v27, v1, s[0:1]
	v_pk_mul_f32 v[14:15], v[102:103], v[14:15]
	v_pk_fma_f32 v[10:11], v[16:17], v[96:97], v[10:11]
	v_cndmask_b32_e64 v2, v28, v2, s[0:1]
	v_cndmask_b32_e64 v3, v29, v3, s[0:1]
	v_pk_fma_f32 v[14:15], v[18:19], v[98:99], v[14:15]
	v_pk_fma_f32 v[0:1], v[92:93], v[0:1], v[10:11]
	v_pk_fma_f32 v[2:3], v[94:95], v[2:3], v[14:15]
	v_mov_b32_dpp v10, v20 row_ror:15 row_mask:0xf bank_mask:0xf
	v_mov_b32_dpp v11, v21 row_ror:15 row_mask:0xf bank_mask:0xf
	v_cndmask_b32_e64 v4, v10, v4, s[0:1]
	v_mov_b32_dpp v14, v22 row_ror:15 row_mask:0xf bank_mask:0xf
	v_mov_b32_dpp v15, v23 row_ror:15 row_mask:0xf bank_mask:0xf
	v_cndmask_b32_e64 v5, v11, v5, s[0:1]
	v_pk_mul_f32 v[10:11], v[74:75], v[12:13]
	v_pk_mul_f32 v[8:9], v[72:73], v[8:9]
	v_cndmask_b32_e64 v6, v14, v6, s[0:1]
	v_cndmask_b32_e64 v7, v15, v7, s[0:1]
	v_pk_fma_f32 v[10:11], v[22:23], v[66:67], v[10:11]
	v_pk_fma_f32 v[8:9], v[20:21], v[64:65], v[8:9]
	v_pk_fma_f32 v[6:7], v[70:71], v[6:7], v[10:11]
	v_pk_fma_f32 v[4:5], v[68:69], v[4:5], v[8:9]
	v_pk_add_f32 v[0:1], v[88:89], v[0:1]
	v_pk_add_f32 v[2:3], v[90:91], v[2:3]
	v_pk_add_f32 v[6:7], v[78:79], v[6:7]
	v_pk_add_f32 v[4:5], v[76:77], v[4:5]
	s_and_saveexec_b64 s[12:13], s[26:27]
	s_cbranch_execz .LBB0_1521
	v_mul_f32_e32 v8, 0xbfb8aa3b, v0
	v_mul_f32_e32 v9, 0xbfb8aa3b, v1
	v_mul_f32_e32 v10, 0xbfb8aa3b, v2
	v_mul_f32_e32 v11, 0xbfb8aa3b, v3
	v_exp_f32_e32 v8, v8
	v_exp_f32_e32 v9, v9
	v_exp_f32_e32 v10, v10
	v_exp_f32_e32 v11, v11
	v_add_f32_e32 v8, 1.0, v8
	v_add_f32_e32 v9, 1.0, v9
	v_add_f32_e32 v10, 1.0, v10
	v_add_f32_e32 v11, 1.0, v11
	v_rcp_f32_e32 v8, v8
	v_rcp_f32_e32 v9, v9
	v_rcp_f32_e32 v10, v10
	v_rcp_f32_e32 v11, v11
	v_pk_mul_f32 v[8:9], v[0:1], v[8:9]
	s_nop 0
	v_pk_mul_f32 v[8:9], v[8:9], v[4:5]
	v_pk_mul_f32 v[10:11], v[2:3], v[10:11]
	v_cvt_pk_bf16_f32 v8, v8, v9
	v_pk_mul_f32 v[10:11], v[10:11], v[6:7]
	s_nop 0
	v_cvt_pk_bf16_f32 v9, v10, v11
	v_mov_b64_e32 v[10:11], s[52:53]
	v_mad_i64_i32 v[10:11], s[8:9], v121, s39, v[10:11]
	v_lshl_add_u64 v[10:11], v[196:197], 1, v[10:11]
	global_store_dwordx2 v[10:11], v[8:9], off offset:32
